# v077 + in-projection epilogue: cross-lane sums via v_permlane16_swap / v_permlane32_swap instead of ds_bpermute (bit-identical)
# baseline (speedup 1.0000x reference)
.LBB0_242:
	s_and_b32 s33, s14, 1
	s_cmp_lg_u32 s6, 2
	s_cselect_b64 s[14:15], -1, 0
	s_cmp_eq_u32 s6, 4
	v_cndmask_b32_e64 v159, 0, 1, s[14:15]
	s_cselect_b64 s[76:77], -1, 0
	s_lshl_b32 s69, s33, 2
	s_waitcnt lgkmcnt(0)
	v_pk_mul_f32 v[144:145], v[144:145], v[160:161] op_sel_hi:[1,0]
	v_pk_mul_f32 v[146:147], v[146:147], v[160:161] op_sel_hi:[1,0]
	v_pk_mul_f32 v[140:141], v[140:141], v[160:161] op_sel_hi:[1,0]
	v_pk_mul_f32 v[142:143], v[142:143], v[160:161] op_sel_hi:[1,0]
	v_pk_mul_f32 v[136:137], v[136:137], v[160:161] op_sel_hi:[1,0]
	v_pk_mul_f32 v[138:139], v[138:139], v[160:161] op_sel_hi:[1,0]
	v_pk_mul_f32 v[132:133], v[132:133], v[160:161] op_sel_hi:[1,0]
	v_pk_mul_f32 v[134:135], v[134:135], v[160:161] op_sel_hi:[1,0]
	s_mov_b64 s[16:17], -1
	s_and_b64 vcc, exec, s[78:79]
	v_cmp_ne_u32_e64 s[14:15], 1, v159
	s_cbranch_vccz .LBB0_249
	s_and_b64 vcc, exec, s[14:15]
	v_mov_b64_e32 v[160:161], v[144:145]
	v_mov_b64_e32 v[162:163], v[146:147]
	v_mov_b64_e32 v[164:165], v[140:141]
	v_mov_b64_e32 v[174:175], v[142:143]
	v_mov_b64_e32 v[176:177], v[136:137]
	v_mov_b64_e32 v[178:179], v[138:139]
	v_mov_b64_e32 v[180:181], v[132:133]
	v_mov_b64_e32 v[182:183], v[134:135]
	s_cbranch_vccnz .LBB0_248
	v_mul_f32_e32 v159, 0x3d922279, v144
	v_fmaak_f32 v159, v144, v159, 0x3fcc422a
	v_mul_f32_e32 v160, 0x3d922279, v145
	v_mul_f32_e32 v159, v144, v159
	v_fmaak_f32 v160, v145, v160, 0x3fcc422a
	v_mul_f32_e32 v159, 0xbfb8aa3b, v159
	v_mul_f32_e32 v160, v145, v160
	v_exp_f32_e32 v159, v159
	v_mul_f32_e32 v160, 0xbfb8aa3b, v160
	v_exp_f32_e32 v161, v160
	v_mul_f32_e32 v162, 0x3d922279, v147
	v_add_f32_e32 v159, 1.0, v159
	v_rcp_f32_e32 v160, v159
	v_add_f32_e32 v159, 1.0, v161
	v_rcp_f32_e32 v161, v159
	v_mul_f32_e32 v159, 0x3d922279, v146
	v_fmaak_f32 v159, v146, v159, 0x3fcc422a
	v_mul_f32_e32 v159, v146, v159
	v_fmaak_f32 v162, v147, v162, 0x3fcc422a
	v_mul_f32_e32 v159, 0xbfb8aa3b, v159
	v_mul_f32_e32 v162, v147, v162
	v_exp_f32_e32 v159, v159
	v_mul_f32_e32 v162, 0xbfb8aa3b, v162
	v_exp_f32_e32 v163, v162
	v_mul_f32_e32 v164, 0x3d922279, v141
	v_add_f32_e32 v159, 1.0, v159
	v_rcp_f32_e32 v162, v159
	v_add_f32_e32 v159, 1.0, v163
	v_rcp_f32_e32 v163, v159
	v_mul_f32_e32 v159, 0x3d922279, v140
	v_fmaak_f32 v159, v140, v159, 0x3fcc422a
	v_mul_f32_e32 v159, v140, v159
	v_fmaak_f32 v164, v141, v164, 0x3fcc422a
	v_mul_f32_e32 v159, 0xbfb8aa3b, v159
	v_mul_f32_e32 v164, v141, v164
	v_exp_f32_e32 v159, v159
	v_mul_f32_e32 v164, 0xbfb8aa3b, v164
	v_exp_f32_e32 v165, v164
	v_mul_f32_e32 v168, 0x3d922279, v143
	v_add_f32_e32 v159, 1.0, v159
	v_rcp_f32_e32 v164, v159
	v_add_f32_e32 v159, 1.0, v165
	v_rcp_f32_e32 v165, v159
	v_mul_f32_e32 v159, 0x3d922279, v142
	v_fmaak_f32 v159, v142, v159, 0x3fcc422a
	v_mul_f32_e32 v159, v142, v159
	v_fmaak_f32 v168, v143, v168, 0x3fcc422a
	v_mul_f32_e32 v159, 0xbfb8aa3b, v159
	v_mul_f32_e32 v168, v143, v168
	v_exp_f32_e32 v159, v159
	v_mul_f32_e32 v168, 0xbfb8aa3b, v168
	v_exp_f32_e32 v169, v168
	v_mul_f32_e32 v170, 0x3d922279, v137
	v_add_f32_e32 v159, 1.0, v159
	v_rcp_f32_e32 v168, v159
	v_add_f32_e32 v159, 1.0, v169
	v_rcp_f32_e32 v169, v159
	v_mul_f32_e32 v159, 0x3d922279, v136
	v_fmaak_f32 v159, v136, v159, 0x3fcc422a
	v_mul_f32_e32 v159, v136, v159
	v_fmaak_f32 v170, v137, v170, 0x3fcc422a
	v_mul_f32_e32 v159, 0xbfb8aa3b, v159
	v_mul_f32_e32 v170, v137, v170
	v_exp_f32_e32 v159, v159
	v_mul_f32_e32 v170, 0xbfb8aa3b, v170
	v_exp_f32_e32 v170, v170
	v_pk_mul_f32 v[174:175], v[142:143], v[168:169]
	v_add_f32_e32 v159, 1.0, v159
	v_rcp_f32_e32 v168, v159
	v_add_f32_e32 v159, 1.0, v170
	v_rcp_f32_e32 v169, v159
	v_mul_f32_e32 v159, 0x3d922279, v138
	v_fmaak_f32 v159, v138, v159, 0x3fcc422a
	v_mul_f32_e32 v170, 0x3d922279, v139
	v_mul_f32_e32 v159, v138, v159
	v_fmaak_f32 v170, v139, v170, 0x3fcc422a
	v_mul_f32_e32 v159, 0xbfb8aa3b, v159
	v_mul_f32_e32 v170, v139, v170
	v_exp_f32_e32 v159, v159
	v_mul_f32_e32 v170, 0xbfb8aa3b, v170
	v_exp_f32_e32 v170, v170
	v_pk_mul_f32 v[176:177], v[136:137], v[168:169]
	v_add_f32_e32 v159, 1.0, v159
	v_rcp_f32_e32 v168, v159
	v_add_f32_e32 v159, 1.0, v170
	v_rcp_f32_e32 v169, v159
	v_mul_f32_e32 v159, 0x3d922279, v132
	v_fmaak_f32 v159, v132, v159, 0x3fcc422a
	v_mul_f32_e32 v170, 0x3d922279, v133
	v_mul_f32_e32 v159, v132, v159
	v_fmaak_f32 v170, v133, v170, 0x3fcc422a
	v_mul_f32_e32 v159, 0xbfb8aa3b, v159
	v_mul_f32_e32 v170, v133, v170
	v_exp_f32_e32 v159, v159
	v_mul_f32_e32 v170, 0xbfb8aa3b, v170
	v_exp_f32_e32 v170, v170
	v_pk_mul_f32 v[178:179], v[138:139], v[168:169]
	v_add_f32_e32 v159, 1.0, v159
	v_rcp_f32_e32 v168, v159
	v_add_f32_e32 v159, 1.0, v170
	v_rcp_f32_e32 v169, v159
	v_mul_f32_e32 v159, 0x3d922279, v134
	v_fmaak_f32 v159, v134, v159, 0x3fcc422a
	v_mul_f32_e32 v170, 0x3d922279, v135
	v_mul_f32_e32 v159, v134, v159
	v_fmaak_f32 v170, v135, v170, 0x3fcc422a
	v_mul_f32_e32 v159, 0xbfb8aa3b, v159
	v_mul_f32_e32 v170, v135, v170
	v_exp_f32_e32 v159, v159
	v_mul_f32_e32 v170, 0xbfb8aa3b, v170
	v_exp_f32_e32 v170, v170
	v_pk_mul_f32 v[180:181], v[132:133], v[168:169]
	v_add_f32_e32 v159, 1.0, v159
	v_rcp_f32_e32 v168, v159
	v_add_f32_e32 v159, 1.0, v170
	v_rcp_f32_e32 v169, v159
	v_pk_mul_f32 v[160:161], v[144:145], v[160:161]
	v_pk_mul_f32 v[162:163], v[146:147], v[162:163]
	v_pk_mul_f32 v[164:165], v[140:141], v[164:165]
	s_andn2_b64 vcc, exec, s[76:77]
	v_pk_mul_f32 v[182:183], v[134:135], v[168:169]
	s_cbranch_vccnz .LBB0_248
	v_pk_mul_f32 v[168:169], v[160:161], v[160:161]
	v_pk_mul_f32 v[170:171], v[162:163], v[162:163]
	v_add_f32_e32 v159, v168, v169
	v_add_f32_e32 v159, v170, v159
	v_pk_mul_f32 v[208:209], v[164:165], v[164:165]
	v_add_f32_e32 v159, v171, v159
	v_add_f32_e32 v159, v208, v159
	v_pk_mul_f32 v[210:211], v[174:175], v[174:175]
	v_add_f32_e32 v159, v209, v159
	v_add_f32_e32 v159, v210, v159
	v_pk_mul_f32 v[212:213], v[176:177], v[176:177]
	v_add_f32_e32 v159, v211, v159
	v_add_f32_e32 v159, v212, v159
	v_pk_mul_f32 v[214:215], v[178:179], v[178:179]
	v_add_f32_e32 v159, v213, v159
	v_add_f32_e32 v159, v214, v159
	v_pk_mul_f32 v[216:217], v[180:181], v[180:181]
	v_add_f32_e32 v159, v215, v159
	v_and_b32_e32 v169, 64, v196
	v_add_f32_e32 v159, v216, v159
	v_xor_b32_e32 v168, 16, v196
	v_add_u32_e32 v169, 64, v169
	v_pk_mul_f32 v[218:219], v[182:183], v[182:183]
	v_add_f32_e32 v159, v217, v159
	v_cmp_lt_i32_e32 vcc, v168, v169
	v_add_f32_e32 v159, v218, v159
	v_add_f32_e32 v159, v219, v159
	v_cndmask_b32_e32 v168, v196, v168, vcc
	v_lshlrev_b32_e32 v168, 2, v168
	v_mov_b32_e32 v168, v159
	s_nop 1
	v_permlane16_swap_b32_e32 v168, v159
	s_waitcnt lgkmcnt(0)
	v_add_f32_e32 v207, v159, v168
	v_xor_b32_e32 v159, 32, v196
	v_cmp_lt_i32_e32 vcc, v159, v169
	s_nop 1
	v_cndmask_b32_e32 v159, v196, v159, vcc
	v_lshlrev_b32_e32 v159, 2, v159
	v_mov_b32_e32 v208, v207
	s_nop 1
	v_permlane32_swap_b32_e32 v208, v207
	s_and_saveexec_b64 s[16:17], s[10:11]
	s_cbranch_execz .LBB0_247
	v_ashrrev_i32_e32 v159, 31, v158
	v_lshlrev_b64 v[168:169], 5, v[158:159]
	v_lshl_add_u64 v[168:169], s[64:65], 0, v[168:169]
	s_lshl_b32 s24, s69, 2
	v_lshl_add_u64 v[168:169], v[168:169], 0, s[24:25]
	s_lshl_b32 s24, s21, 2
	v_lshl_add_u64 v[168:169], v[168:169], 0, s[24:25]
	s_waitcnt lgkmcnt(0)
	v_add_f32_e32 v159, v207, v208
	global_store_dword v[168:169], v159, off

.LBB0_249:
	s_andn2_b64 vcc, exec, s[16:17]
	s_cbranch_vccnz .LBB0_251
	v_pk_mul_f32 v[160:161], v[144:145], v[144:145]
	v_pk_mul_f32 v[162:163], v[146:147], v[146:147]
	v_add_f32_e32 v159, v160, v161
	v_add_f32_e32 v159, v162, v159
	v_pk_mul_f32 v[164:165], v[140:141], v[140:141]
	v_add_f32_e32 v159, v163, v159
	v_add_f32_e32 v159, v164, v159
	v_pk_mul_f32 v[168:169], v[142:143], v[142:143]
	v_add_f32_e32 v159, v165, v159
	v_add_f32_e32 v159, v168, v159
	v_pk_mul_f32 v[170:171], v[136:137], v[136:137]
	v_add_f32_e32 v159, v169, v159
	v_add_f32_e32 v159, v170, v159
	v_pk_mul_f32 v[174:175], v[138:139], v[138:139]
	v_add_f32_e32 v159, v171, v159
	v_add_f32_e32 v159, v174, v159
	v_mbcnt_hi_u32_b32 v160, -1, v1
	v_pk_mul_f32 v[176:177], v[132:133], v[132:133]
	v_add_f32_e32 v159, v175, v159
	v_and_b32_e32 v162, 64, v160
	v_add_f32_e32 v159, v176, v159
	v_xor_b32_e32 v161, 16, v160
	v_add_u32_e32 v162, 64, v162
	v_pk_mul_f32 v[178:179], v[134:135], v[134:135]
	v_add_f32_e32 v159, v177, v159
	v_cmp_lt_i32_e32 vcc, v161, v162
	v_add_f32_e32 v159, v178, v159
	v_add_f32_e32 v159, v179, v159
	v_cndmask_b32_e32 v161, v160, v161, vcc
	v_lshlrev_b32_e32 v161, 2, v161
	v_mov_b32_e32 v161, v159
	s_nop 1
	v_permlane16_swap_b32_e32 v161, v159
	s_waitcnt lgkmcnt(0)
	v_add_f32_e32 v159, v159, v161
	v_xor_b32_e32 v161, 32, v160
	v_cmp_lt_i32_e32 vcc, v161, v162
	s_nop 1
	v_cndmask_b32_e32 v160, v160, v161, vcc
	v_lshlrev_b32_e32 v160, 2, v160
	v_mov_b32_e32 v160, v159
	s_nop 1
	v_permlane32_swap_b32_e32 v160, v159
	s_waitcnt lgkmcnt(0)
	v_add_f32_e32 v159, v159, v160
	v_fmamk_f32 v159, v159, 0x3c800000, v193
	v_rsq_f32_e32 v168, v159
	s_nop 0
	v_pk_mul_f32 v[144:145], v[144:145], v[168:169] op_sel_hi:[1,0]
	v_pk_mul_f32 v[140:141], v[140:141], v[168:169] op_sel_hi:[1,0]
	v_pk_mul_f32 v[136:137], v[136:137], v[168:169] op_sel_hi:[1,0]
	v_pk_mul_f32 v[132:133], v[132:133], v[168:169] op_sel_hi:[1,0]
	v_pk_mul_f32 v[160:161], v[36:37], v[144:145]
	v_pk_mul_f32 v[144:145], v[146:147], v[168:169] op_sel_hi:[1,0]
	v_pk_mul_f32 v[164:165], v[24:25], v[140:141]
	v_pk_mul_f32 v[140:141], v[142:143], v[168:169] op_sel_hi:[1,0]
	v_pk_mul_f32 v[176:177], v[28:29], v[136:137]
	v_pk_mul_f32 v[136:137], v[138:139], v[168:169] op_sel_hi:[1,0]
	v_pk_mul_f32 v[180:181], v[20:21], v[132:133]
	v_pk_mul_f32 v[132:133], v[134:135], v[168:169] op_sel_hi:[1,0]
	v_pk_mul_f32 v[162:163], v[38:39], v[144:145]
	v_pk_mul_f32 v[174:175], v[26:27], v[140:141]
	v_pk_mul_f32 v[178:179], v[30:31], v[136:137]
	v_pk_mul_f32 v[182:183], v[22:23], v[132:133]

.LBB0_255:
	v_cndmask_b32_e64 v135, 0, 1, s[78:79]
	s_waitcnt lgkmcnt(0)
	v_pk_mul_f32 v[128:129], v[128:129], v[136:137] op_sel_hi:[1,0]
	v_pk_mul_f32 v[130:131], v[130:131], v[136:137] op_sel_hi:[1,0]
	v_pk_mul_f32 v[124:125], v[124:125], v[136:137] op_sel_hi:[1,0]
	v_pk_mul_f32 v[126:127], v[126:127], v[136:137] op_sel_hi:[1,0]
	v_pk_mul_f32 v[120:121], v[120:121], v[136:137] op_sel_hi:[1,0]
	v_pk_mul_f32 v[122:123], v[122:123], v[136:137] op_sel_hi:[1,0]
	v_pk_mul_f32 v[116:117], v[116:117], v[136:137] op_sel_hi:[1,0]
	v_pk_mul_f32 v[118:119], v[118:119], v[136:137] op_sel_hi:[1,0]
	v_cmp_ne_u32_e64 s[18:19], 1, v135
	s_andn2_b64 vcc, exec, s[78:79]
	s_mov_b64 s[78:79], -1
	s_cbranch_vccnz .LBB0_262
	s_and_b64 vcc, exec, s[14:15]
	v_mov_b64_e32 v[136:137], v[128:129]
	v_mov_b64_e32 v[138:139], v[130:131]
	v_mov_b64_e32 v[140:141], v[124:125]
	v_mov_b64_e32 v[142:143], v[126:127]
	v_mov_b64_e32 v[144:145], v[120:121]
	v_mov_b64_e32 v[146:147], v[122:123]
	v_mov_b64_e32 v[158:159], v[116:117]
	v_mov_b64_e32 v[160:161], v[118:119]
	s_cbranch_vccnz .LBB0_261
	v_mul_f32_e32 v135, 0x3d922279, v128
	v_fmaak_f32 v135, v128, v135, 0x3fcc422a
	v_mul_f32_e32 v136, 0x3d922279, v129
	v_mul_f32_e32 v135, v128, v135
	v_fmaak_f32 v136, v129, v136, 0x3fcc422a
	v_mul_f32_e32 v135, 0xbfb8aa3b, v135
	v_mul_f32_e32 v136, v129, v136
	v_exp_f32_e32 v135, v135
	v_mul_f32_e32 v136, 0xbfb8aa3b, v136
	v_exp_f32_e32 v137, v136
	v_mul_f32_e32 v138, 0x3d922279, v131
	v_add_f32_e32 v135, 1.0, v135
	v_rcp_f32_e32 v136, v135
	v_add_f32_e32 v135, 1.0, v137
	v_rcp_f32_e32 v137, v135
	v_mul_f32_e32 v135, 0x3d922279, v130
	v_fmaak_f32 v135, v130, v135, 0x3fcc422a
	v_mul_f32_e32 v135, v130, v135
	v_fmaak_f32 v138, v131, v138, 0x3fcc422a
	v_mul_f32_e32 v135, 0xbfb8aa3b, v135
	v_mul_f32_e32 v138, v131, v138
	v_exp_f32_e32 v135, v135
	v_mul_f32_e32 v138, 0xbfb8aa3b, v138
	v_exp_f32_e32 v139, v138
	v_mul_f32_e32 v140, 0x3d922279, v125
	v_add_f32_e32 v135, 1.0, v135
	v_rcp_f32_e32 v138, v135
	v_add_f32_e32 v135, 1.0, v139
	v_rcp_f32_e32 v139, v135
	v_mul_f32_e32 v135, 0x3d922279, v124
	v_fmaak_f32 v135, v124, v135, 0x3fcc422a
	v_mul_f32_e32 v135, v124, v135
	v_fmaak_f32 v140, v125, v140, 0x3fcc422a
	v_mul_f32_e32 v135, 0xbfb8aa3b, v135
	v_mul_f32_e32 v140, v125, v140
	v_exp_f32_e32 v135, v135
	v_mul_f32_e32 v140, 0xbfb8aa3b, v140
	v_exp_f32_e32 v141, v140
	v_mul_f32_e32 v142, 0x3d922279, v127
	v_add_f32_e32 v135, 1.0, v135
	v_rcp_f32_e32 v140, v135
	v_add_f32_e32 v135, 1.0, v141
	v_rcp_f32_e32 v141, v135
	v_mul_f32_e32 v135, 0x3d922279, v126
	v_fmaak_f32 v135, v126, v135, 0x3fcc422a
	v_mul_f32_e32 v135, v126, v135
	v_fmaak_f32 v142, v127, v142, 0x3fcc422a
	v_mul_f32_e32 v135, 0xbfb8aa3b, v135
	v_mul_f32_e32 v142, v127, v142
	v_exp_f32_e32 v135, v135
	v_mul_f32_e32 v142, 0xbfb8aa3b, v142
	v_exp_f32_e32 v143, v142
	v_mul_f32_e32 v144, 0x3d922279, v121
	v_add_f32_e32 v135, 1.0, v135
	v_rcp_f32_e32 v142, v135
	v_add_f32_e32 v135, 1.0, v143
	v_rcp_f32_e32 v143, v135
	v_mul_f32_e32 v135, 0x3d922279, v120
	v_fmaak_f32 v135, v120, v135, 0x3fcc422a
	v_mul_f32_e32 v135, v120, v135
	v_fmaak_f32 v144, v121, v144, 0x3fcc422a
	v_mul_f32_e32 v135, 0xbfb8aa3b, v135
	v_mul_f32_e32 v144, v121, v144
	v_exp_f32_e32 v135, v135
	v_mul_f32_e32 v144, 0xbfb8aa3b, v144
	v_exp_f32_e32 v145, v144
	v_mul_f32_e32 v146, 0x3d922279, v123
	v_add_f32_e32 v135, 1.0, v135
	v_rcp_f32_e32 v144, v135
	v_add_f32_e32 v135, 1.0, v145
	v_rcp_f32_e32 v145, v135
	v_mul_f32_e32 v135, 0x3d922279, v122
	v_fmaak_f32 v135, v122, v135, 0x3fcc422a
	v_mul_f32_e32 v135, v122, v135
	v_fmaak_f32 v146, v123, v146, 0x3fcc422a
	v_mul_f32_e32 v135, 0xbfb8aa3b, v135
	v_mul_f32_e32 v146, v123, v146
	v_exp_f32_e32 v135, v135
	v_mul_f32_e32 v146, 0xbfb8aa3b, v146
	v_exp_f32_e32 v147, v146
	v_mul_f32_e32 v158, 0x3d922279, v117
	v_add_f32_e32 v135, 1.0, v135
	v_rcp_f32_e32 v146, v135
	v_add_f32_e32 v135, 1.0, v147
	v_rcp_f32_e32 v147, v135
	v_mul_f32_e32 v135, 0x3d922279, v116
	v_fmaak_f32 v135, v116, v135, 0x3fcc422a
	v_mul_f32_e32 v135, v116, v135
	v_fmaak_f32 v158, v117, v158, 0x3fcc422a
	v_mul_f32_e32 v135, 0xbfb8aa3b, v135
	v_mul_f32_e32 v158, v117, v158
	v_exp_f32_e32 v135, v135
	v_mul_f32_e32 v158, 0xbfb8aa3b, v158
	v_exp_f32_e32 v159, v158
	v_mul_f32_e32 v160, 0x3d922279, v119
	v_add_f32_e32 v135, 1.0, v135
	v_rcp_f32_e32 v158, v135
	v_add_f32_e32 v135, 1.0, v159
	v_rcp_f32_e32 v159, v135
	v_mul_f32_e32 v135, 0x3d922279, v118
	v_fmaak_f32 v135, v118, v135, 0x3fcc422a
	v_mul_f32_e32 v135, v118, v135
	v_fmaak_f32 v160, v119, v160, 0x3fcc422a
	v_mul_f32_e32 v135, 0xbfb8aa3b, v135
	v_mul_f32_e32 v160, v119, v160
	v_exp_f32_e32 v135, v135
	v_mul_f32_e32 v160, 0xbfb8aa3b, v160
	v_exp_f32_e32 v161, v160
	v_pk_mul_f32 v[136:137], v[128:129], v[136:137]
	v_add_f32_e32 v135, 1.0, v135
	v_rcp_f32_e32 v160, v135
	v_add_f32_e32 v135, 1.0, v161
	v_rcp_f32_e32 v161, v135
	v_pk_mul_f32 v[138:139], v[130:131], v[138:139]
	v_pk_mul_f32 v[140:141], v[124:125], v[140:141]
	v_pk_mul_f32 v[142:143], v[126:127], v[142:143]
	v_pk_mul_f32 v[144:145], v[120:121], v[144:145]
	v_pk_mul_f32 v[146:147], v[122:123], v[146:147]
	v_pk_mul_f32 v[158:159], v[116:117], v[158:159]
	s_andn2_b64 vcc, exec, s[76:77]
	v_pk_mul_f32 v[160:161], v[118:119], v[160:161]
	s_cbranch_vccnz .LBB0_261
	v_pk_mul_f32 v[162:163], v[136:137], v[136:137]
	v_pk_mul_f32 v[164:165], v[138:139], v[138:139]
	v_add_f32_e32 v135, v162, v163
	v_add_f32_e32 v135, v164, v135
	v_pk_mul_f32 v[168:169], v[140:141], v[140:141]
	v_add_f32_e32 v135, v165, v135
	v_add_f32_e32 v135, v168, v135
	v_pk_mul_f32 v[170:171], v[142:143], v[142:143]
	v_add_f32_e32 v135, v169, v135
	v_add_f32_e32 v135, v170, v135
	v_pk_mul_f32 v[174:175], v[144:145], v[144:145]
	v_add_f32_e32 v135, v171, v135
	v_add_f32_e32 v135, v174, v135
	v_pk_mul_f32 v[176:177], v[146:147], v[146:147]
	v_add_f32_e32 v135, v175, v135
	v_add_f32_e32 v135, v176, v135
	v_mbcnt_hi_u32_b32 v163, -1, v1
	v_pk_mul_f32 v[178:179], v[158:159], v[158:159]
	v_add_f32_e32 v135, v177, v135
	v_and_b32_e32 v164, 64, v163
	v_add_f32_e32 v135, v178, v135
	v_xor_b32_e32 v162, 16, v163
	v_add_u32_e32 v164, 64, v164
	v_pk_mul_f32 v[180:181], v[160:161], v[160:161]
	v_add_f32_e32 v135, v179, v135
	v_cmp_lt_i32_e32 vcc, v162, v164
	v_add_f32_e32 v135, v180, v135
	v_add_f32_e32 v135, v181, v135
	v_cndmask_b32_e32 v162, v163, v162, vcc
	v_lshlrev_b32_e32 v162, 2, v162
	v_mov_b32_e32 v162, v135
	s_nop 1
	v_permlane16_swap_b32_e32 v162, v135
	s_waitcnt lgkmcnt(0)
	v_add_f32_e32 v162, v135, v162
	v_xor_b32_e32 v135, 32, v163
	v_cmp_lt_i32_e32 vcc, v135, v164
	s_nop 1
	v_cndmask_b32_e32 v135, v163, v135, vcc
	v_lshlrev_b32_e32 v135, 2, v135
	v_mov_b32_e32 v163, v162
	s_nop 1
	v_permlane32_swap_b32_e32 v163, v162
	s_and_saveexec_b64 s[78:79], s[10:11]
	s_cbranch_execz .LBB0_260
	v_ashrrev_i32_e32 v135, 31, v134
	v_lshlrev_b64 v[164:165], 5, v[134:135]
	v_lshl_add_u64 v[164:165], s[64:65], 0, v[164:165]
	s_lshl_b32 s24, s69, 2
	v_lshl_add_u64 v[164:165], v[164:165], 0, s[24:25]
	s_lshl_b32 s24, s21, 2
	v_lshl_add_u64 v[164:165], v[164:165], 0, s[24:25]
	s_waitcnt lgkmcnt(0)
	v_add_f32_e32 v135, v162, v163
	global_store_dword v[164:165], v135, off

.LBB0_262:
	s_andn2_b64 vcc, exec, s[78:79]
	s_cbranch_vccnz .LBB0_264
	v_pk_mul_f32 v[136:137], v[128:129], v[128:129]
	v_pk_mul_f32 v[138:139], v[130:131], v[130:131]
	v_add_f32_e32 v135, v136, v137
	v_add_f32_e32 v135, v138, v135
	v_pk_mul_f32 v[140:141], v[124:125], v[124:125]
	v_add_f32_e32 v135, v139, v135
	v_add_f32_e32 v135, v140, v135
	v_pk_mul_f32 v[142:143], v[126:127], v[126:127]
	v_add_f32_e32 v135, v141, v135
	v_add_f32_e32 v135, v142, v135
	v_pk_mul_f32 v[144:145], v[120:121], v[120:121]
	v_add_f32_e32 v135, v143, v135
	v_add_f32_e32 v135, v144, v135
	v_pk_mul_f32 v[146:147], v[122:123], v[122:123]
	v_add_f32_e32 v135, v145, v135
	v_add_f32_e32 v135, v146, v135
	v_mbcnt_hi_u32_b32 v136, -1, v1
	v_pk_mul_f32 v[158:159], v[116:117], v[116:117]
	v_add_f32_e32 v135, v147, v135
	v_and_b32_e32 v138, 64, v136
	v_add_f32_e32 v135, v158, v135
	v_xor_b32_e32 v137, 16, v136
	v_add_u32_e32 v138, 64, v138
	v_pk_mul_f32 v[160:161], v[118:119], v[118:119]
	v_add_f32_e32 v135, v159, v135
	v_cmp_lt_i32_e32 vcc, v137, v138
	v_add_f32_e32 v135, v160, v135
	v_add_f32_e32 v135, v161, v135
	v_cndmask_b32_e32 v137, v136, v137, vcc
	v_lshlrev_b32_e32 v137, 2, v137
	v_mov_b32_e32 v137, v135
	s_nop 1
	v_permlane16_swap_b32_e32 v137, v135
	s_waitcnt lgkmcnt(0)
	v_add_f32_e32 v135, v135, v137
	v_xor_b32_e32 v137, 32, v136
	v_cmp_lt_i32_e32 vcc, v137, v138
	s_nop 1
	v_cndmask_b32_e32 v136, v136, v137, vcc
	v_lshlrev_b32_e32 v136, 2, v136
	v_mov_b32_e32 v136, v135
	s_nop 1
	v_permlane32_swap_b32_e32 v136, v135
	s_waitcnt lgkmcnt(0)
	v_add_f32_e32 v135, v135, v136
	v_fmamk_f32 v135, v135, 0x3c800000, v193
	v_rsq_f32_e32 v160, v135
	s_nop 0
	v_pk_mul_f32 v[128:129], v[128:129], v[160:161] op_sel_hi:[1,0]
	v_pk_mul_f32 v[124:125], v[124:125], v[160:161] op_sel_hi:[1,0]
	v_pk_mul_f32 v[120:121], v[120:121], v[160:161] op_sel_hi:[1,0]
	v_pk_mul_f32 v[116:117], v[116:117], v[160:161] op_sel_hi:[1,0]
	v_pk_mul_f32 v[136:137], v[36:37], v[128:129]
	v_pk_mul_f32 v[128:129], v[130:131], v[160:161] op_sel_hi:[1,0]
	v_pk_mul_f32 v[140:141], v[24:25], v[124:125]
	v_pk_mul_f32 v[124:125], v[126:127], v[160:161] op_sel_hi:[1,0]
	v_pk_mul_f32 v[144:145], v[28:29], v[120:121]
	v_pk_mul_f32 v[120:121], v[122:123], v[160:161] op_sel_hi:[1,0]
	v_pk_mul_f32 v[158:159], v[20:21], v[116:117]
	v_pk_mul_f32 v[116:117], v[118:119], v[160:161] op_sel_hi:[1,0]
	v_pk_mul_f32 v[138:139], v[38:39], v[128:129]
	v_pk_mul_f32 v[142:143], v[26:27], v[124:125]
	v_pk_mul_f32 v[146:147], v[30:31], v[120:121]
	v_pk_mul_f32 v[160:161], v[22:23], v[116:117]

.LBB0_268:
	s_waitcnt lgkmcnt(0)
	v_pk_mul_f32 v[112:113], v[112:113], v[118:119] op_sel_hi:[1,0]
	v_pk_mul_f32 v[114:115], v[114:115], v[118:119] op_sel_hi:[1,0]
	v_pk_mul_f32 v[108:109], v[108:109], v[118:119] op_sel_hi:[1,0]
	v_pk_mul_f32 v[110:111], v[110:111], v[118:119] op_sel_hi:[1,0]
	v_pk_mul_f32 v[104:105], v[104:105], v[118:119] op_sel_hi:[1,0]
	v_pk_mul_f32 v[106:107], v[106:107], v[118:119] op_sel_hi:[1,0]
	v_pk_mul_f32 v[100:101], v[100:101], v[118:119] op_sel_hi:[1,0]
	v_pk_mul_f32 v[102:103], v[102:103], v[118:119] op_sel_hi:[1,0]
	s_and_b64 vcc, exec, s[18:19]
	s_mov_b64 s[78:79], -1
	s_cbranch_vccnz .LBB0_275
	s_and_b64 vcc, exec, s[14:15]
	v_mov_b64_e32 v[118:119], v[112:113]
	v_mov_b64_e32 v[120:121], v[114:115]
	v_mov_b64_e32 v[122:123], v[108:109]
	v_mov_b64_e32 v[124:125], v[110:111]
	v_mov_b64_e32 v[126:127], v[104:105]
	v_mov_b64_e32 v[128:129], v[106:107]
	v_mov_b64_e32 v[130:131], v[100:101]
	v_mov_b64_e32 v[134:135], v[102:103]
	s_cbranch_vccnz .LBB0_274
	v_mul_f32_e32 v117, 0x3d922279, v112
	v_fmaak_f32 v117, v112, v117, 0x3fcc422a
	v_mul_f32_e32 v118, 0x3d922279, v113
	v_mul_f32_e32 v117, v112, v117
	v_fmaak_f32 v118, v113, v118, 0x3fcc422a
	v_mul_f32_e32 v117, 0xbfb8aa3b, v117
	v_mul_f32_e32 v118, v113, v118
	v_exp_f32_e32 v117, v117
	v_mul_f32_e32 v118, 0xbfb8aa3b, v118
	v_exp_f32_e32 v119, v118
	v_mul_f32_e32 v120, 0x3d922279, v115
	v_add_f32_e32 v117, 1.0, v117
	v_rcp_f32_e32 v118, v117
	v_add_f32_e32 v117, 1.0, v119
	v_rcp_f32_e32 v119, v117
	v_mul_f32_e32 v117, 0x3d922279, v114
	v_fmaak_f32 v117, v114, v117, 0x3fcc422a
	v_mul_f32_e32 v117, v114, v117
	v_fmaak_f32 v120, v115, v120, 0x3fcc422a
	v_mul_f32_e32 v117, 0xbfb8aa3b, v117
	v_mul_f32_e32 v120, v115, v120
	v_exp_f32_e32 v117, v117
	v_mul_f32_e32 v120, 0xbfb8aa3b, v120
	v_exp_f32_e32 v121, v120
	v_mul_f32_e32 v122, 0x3d922279, v109
	v_add_f32_e32 v117, 1.0, v117
	v_rcp_f32_e32 v120, v117
	v_add_f32_e32 v117, 1.0, v121
	v_rcp_f32_e32 v121, v117
	v_mul_f32_e32 v117, 0x3d922279, v108
	v_fmaak_f32 v117, v108, v117, 0x3fcc422a
	v_mul_f32_e32 v117, v108, v117
	v_fmaak_f32 v122, v109, v122, 0x3fcc422a
	v_mul_f32_e32 v117, 0xbfb8aa3b, v117
	v_mul_f32_e32 v122, v109, v122
	v_exp_f32_e32 v117, v117
	v_mul_f32_e32 v122, 0xbfb8aa3b, v122
	v_exp_f32_e32 v123, v122
	v_mul_f32_e32 v124, 0x3d922279, v111
	v_add_f32_e32 v117, 1.0, v117
	v_rcp_f32_e32 v122, v117
	v_add_f32_e32 v117, 1.0, v123
	v_rcp_f32_e32 v123, v117
	v_mul_f32_e32 v117, 0x3d922279, v110
	v_fmaak_f32 v117, v110, v117, 0x3fcc422a
	v_mul_f32_e32 v117, v110, v117
	v_fmaak_f32 v124, v111, v124, 0x3fcc422a
	v_mul_f32_e32 v117, 0xbfb8aa3b, v117
	v_mul_f32_e32 v124, v111, v124
	v_exp_f32_e32 v117, v117
	v_mul_f32_e32 v124, 0xbfb8aa3b, v124
	v_exp_f32_e32 v125, v124
	v_mul_f32_e32 v126, 0x3d922279, v105
	v_add_f32_e32 v117, 1.0, v117
	v_rcp_f32_e32 v124, v117
	v_add_f32_e32 v117, 1.0, v125
	v_rcp_f32_e32 v125, v117
	v_mul_f32_e32 v117, 0x3d922279, v104
	v_fmaak_f32 v117, v104, v117, 0x3fcc422a
	v_mul_f32_e32 v117, v104, v117
	v_fmaak_f32 v126, v105, v126, 0x3fcc422a
	v_mul_f32_e32 v117, 0xbfb8aa3b, v117
	v_mul_f32_e32 v126, v105, v126
	v_exp_f32_e32 v117, v117
	v_mul_f32_e32 v126, 0xbfb8aa3b, v126
	v_exp_f32_e32 v127, v126
	v_mul_f32_e32 v128, 0x3d922279, v107
	v_add_f32_e32 v117, 1.0, v117
	v_rcp_f32_e32 v126, v117
	v_add_f32_e32 v117, 1.0, v127
	v_rcp_f32_e32 v127, v117
	v_mul_f32_e32 v117, 0x3d922279, v106
	v_fmaak_f32 v117, v106, v117, 0x3fcc422a
	v_mul_f32_e32 v117, v106, v117
	v_fmaak_f32 v128, v107, v128, 0x3fcc422a
	v_mul_f32_e32 v117, 0xbfb8aa3b, v117
	v_mul_f32_e32 v128, v107, v128
	v_exp_f32_e32 v117, v117
	v_mul_f32_e32 v128, 0xbfb8aa3b, v128
	v_exp_f32_e32 v129, v128
	v_mul_f32_e32 v130, 0x3d922279, v101
	v_add_f32_e32 v117, 1.0, v117
	v_rcp_f32_e32 v128, v117
	v_add_f32_e32 v117, 1.0, v129
	v_rcp_f32_e32 v129, v117
	v_mul_f32_e32 v117, 0x3d922279, v100
	v_fmaak_f32 v117, v100, v117, 0x3fcc422a
	v_mul_f32_e32 v117, v100, v117
	v_fmaak_f32 v130, v101, v130, 0x3fcc422a
	v_mul_f32_e32 v117, 0xbfb8aa3b, v117
	v_mul_f32_e32 v130, v101, v130
	v_exp_f32_e32 v117, v117
	v_mul_f32_e32 v130, 0xbfb8aa3b, v130
	v_exp_f32_e32 v131, v130
	v_mul_f32_e32 v134, 0x3d922279, v103
	v_add_f32_e32 v117, 1.0, v117
	v_rcp_f32_e32 v130, v117
	v_add_f32_e32 v117, 1.0, v131
	v_rcp_f32_e32 v131, v117
	v_mul_f32_e32 v117, 0x3d922279, v102
	v_fmaak_f32 v117, v102, v117, 0x3fcc422a
	v_mul_f32_e32 v117, v102, v117
	v_fmaak_f32 v134, v103, v134, 0x3fcc422a
	v_mul_f32_e32 v117, 0xbfb8aa3b, v117
	v_mul_f32_e32 v134, v103, v134
	v_exp_f32_e32 v117, v117
	v_mul_f32_e32 v134, 0xbfb8aa3b, v134
	v_exp_f32_e32 v135, v134
	v_pk_mul_f32 v[118:119], v[112:113], v[118:119]
	v_add_f32_e32 v117, 1.0, v117
	v_rcp_f32_e32 v134, v117
	v_add_f32_e32 v117, 1.0, v135
	v_rcp_f32_e32 v135, v117
	v_pk_mul_f32 v[120:121], v[114:115], v[120:121]
	v_pk_mul_f32 v[122:123], v[108:109], v[122:123]
	v_pk_mul_f32 v[124:125], v[110:111], v[124:125]
	v_pk_mul_f32 v[126:127], v[104:105], v[126:127]
	v_pk_mul_f32 v[128:129], v[106:107], v[128:129]
	v_pk_mul_f32 v[130:131], v[100:101], v[130:131]
	s_andn2_b64 vcc, exec, s[76:77]
	v_pk_mul_f32 v[134:135], v[102:103], v[134:135]
	s_cbranch_vccnz .LBB0_274
	v_pk_mul_f32 v[136:137], v[118:119], v[118:119]
	v_pk_mul_f32 v[138:139], v[120:121], v[120:121]
	v_add_f32_e32 v117, v136, v137
	v_add_f32_e32 v117, v138, v117
	v_pk_mul_f32 v[140:141], v[122:123], v[122:123]
	v_add_f32_e32 v117, v139, v117
	v_add_f32_e32 v117, v140, v117
	v_pk_mul_f32 v[142:143], v[124:125], v[124:125]
	v_add_f32_e32 v117, v141, v117
	v_add_f32_e32 v117, v142, v117
	v_pk_mul_f32 v[144:145], v[126:127], v[126:127]
	v_add_f32_e32 v117, v143, v117
	v_add_f32_e32 v117, v144, v117
	v_pk_mul_f32 v[146:147], v[128:129], v[128:129]
	v_add_f32_e32 v117, v145, v117
	v_add_f32_e32 v117, v146, v117
	v_mbcnt_hi_u32_b32 v137, -1, v1
	v_pk_mul_f32 v[158:159], v[130:131], v[130:131]
	v_add_f32_e32 v117, v147, v117
	v_and_b32_e32 v138, 64, v137
	v_add_f32_e32 v117, v158, v117
	v_xor_b32_e32 v136, 16, v137
	v_add_u32_e32 v138, 64, v138
	v_pk_mul_f32 v[160:161], v[134:135], v[134:135]
	v_add_f32_e32 v117, v159, v117
	v_cmp_lt_i32_e32 vcc, v136, v138
	v_add_f32_e32 v117, v160, v117
	v_add_f32_e32 v117, v161, v117
	v_cndmask_b32_e32 v136, v137, v136, vcc
	v_lshlrev_b32_e32 v136, 2, v136
	v_mov_b32_e32 v136, v117
	s_nop 1
	v_permlane16_swap_b32_e32 v136, v117
	s_waitcnt lgkmcnt(0)
	v_add_f32_e32 v136, v117, v136
	v_xor_b32_e32 v117, 32, v137
	v_cmp_lt_i32_e32 vcc, v117, v138
	s_nop 1
	v_cndmask_b32_e32 v117, v137, v117, vcc
	v_lshlrev_b32_e32 v117, 2, v117
	v_mov_b32_e32 v137, v136
	s_nop 1
	v_permlane32_swap_b32_e32 v137, v136
	s_and_saveexec_b64 s[78:79], s[10:11]
	s_cbranch_execz .LBB0_273
	v_ashrrev_i32_e32 v117, 31, v116
	v_lshlrev_b64 v[138:139], 5, v[116:117]
	v_lshl_add_u64 v[138:139], s[64:65], 0, v[138:139]
	s_lshl_b32 s24, s69, 2
	v_lshl_add_u64 v[138:139], v[138:139], 0, s[24:25]
	s_lshl_b32 s24, s21, 2
	v_lshl_add_u64 v[138:139], v[138:139], 0, s[24:25]
	s_waitcnt lgkmcnt(0)
	v_add_f32_e32 v117, v136, v137
	global_store_dword v[138:139], v117, off

.LBB0_275:
	s_andn2_b64 vcc, exec, s[78:79]
	s_cbranch_vccnz .LBB0_277
	v_pk_mul_f32 v[118:119], v[112:113], v[112:113]
	v_pk_mul_f32 v[120:121], v[114:115], v[114:115]
	v_add_f32_e32 v117, v118, v119
	v_add_f32_e32 v117, v120, v117
	v_pk_mul_f32 v[122:123], v[108:109], v[108:109]
	v_add_f32_e32 v117, v121, v117
	v_add_f32_e32 v117, v122, v117
	v_pk_mul_f32 v[124:125], v[110:111], v[110:111]
	v_add_f32_e32 v117, v123, v117
	v_add_f32_e32 v117, v124, v117
	v_pk_mul_f32 v[126:127], v[104:105], v[104:105]
	v_add_f32_e32 v117, v125, v117
	v_add_f32_e32 v117, v126, v117
	v_pk_mul_f32 v[128:129], v[106:107], v[106:107]
	v_add_f32_e32 v117, v127, v117
	v_add_f32_e32 v117, v128, v117
	v_mbcnt_hi_u32_b32 v118, -1, v1
	v_pk_mul_f32 v[130:131], v[100:101], v[100:101]
	v_add_f32_e32 v117, v129, v117
	v_and_b32_e32 v120, 64, v118
	v_add_f32_e32 v117, v130, v117
	v_xor_b32_e32 v119, 16, v118
	v_add_u32_e32 v120, 64, v120
	v_pk_mul_f32 v[134:135], v[102:103], v[102:103]
	v_add_f32_e32 v117, v131, v117
	v_cmp_lt_i32_e32 vcc, v119, v120
	v_add_f32_e32 v117, v134, v117
	v_add_f32_e32 v117, v135, v117
	v_cndmask_b32_e32 v119, v118, v119, vcc
	v_lshlrev_b32_e32 v119, 2, v119
	v_mov_b32_e32 v119, v117
	s_nop 1
	v_permlane16_swap_b32_e32 v119, v117
	s_waitcnt lgkmcnt(0)
	v_add_f32_e32 v117, v117, v119
	v_xor_b32_e32 v119, 32, v118
	v_cmp_lt_i32_e32 vcc, v119, v120
	s_nop 1
	v_cndmask_b32_e32 v118, v118, v119, vcc
	v_lshlrev_b32_e32 v118, 2, v118
	v_mov_b32_e32 v118, v117
	s_nop 1
	v_permlane32_swap_b32_e32 v118, v117
	s_waitcnt lgkmcnt(0)
	v_add_f32_e32 v117, v117, v118
	v_fmamk_f32 v117, v117, 0x3c800000, v193
	v_rsq_f32_e32 v134, v117
	s_nop 0
	v_pk_mul_f32 v[112:113], v[112:113], v[134:135] op_sel_hi:[1,0]
	v_pk_mul_f32 v[108:109], v[108:109], v[134:135] op_sel_hi:[1,0]
	v_pk_mul_f32 v[104:105], v[104:105], v[134:135] op_sel_hi:[1,0]
	v_pk_mul_f32 v[100:101], v[100:101], v[134:135] op_sel_hi:[1,0]
	v_pk_mul_f32 v[118:119], v[36:37], v[112:113]
	v_pk_mul_f32 v[112:113], v[114:115], v[134:135] op_sel_hi:[1,0]
	v_pk_mul_f32 v[122:123], v[24:25], v[108:109]
	v_pk_mul_f32 v[108:109], v[110:111], v[134:135] op_sel_hi:[1,0]
	v_pk_mul_f32 v[126:127], v[28:29], v[104:105]
	v_pk_mul_f32 v[104:105], v[106:107], v[134:135] op_sel_hi:[1,0]
	v_pk_mul_f32 v[130:131], v[20:21], v[100:101]
	v_pk_mul_f32 v[100:101], v[102:103], v[134:135] op_sel_hi:[1,0]
	v_pk_mul_f32 v[120:121], v[38:39], v[112:113]
	v_pk_mul_f32 v[124:125], v[26:27], v[108:109]
	v_pk_mul_f32 v[128:129], v[30:31], v[104:105]
	v_pk_mul_f32 v[134:135], v[22:23], v[100:101]

.LBB0_281:
	s_waitcnt lgkmcnt(0)
	v_pk_mul_f32 v[96:97], v[96:97], v[102:103] op_sel_hi:[1,0]
	v_pk_mul_f32 v[98:99], v[98:99], v[102:103] op_sel_hi:[1,0]
	v_pk_mul_f32 v[92:93], v[92:93], v[102:103] op_sel_hi:[1,0]
	v_pk_mul_f32 v[94:95], v[94:95], v[102:103] op_sel_hi:[1,0]
	v_pk_mul_f32 v[88:89], v[88:89], v[102:103] op_sel_hi:[1,0]
	v_pk_mul_f32 v[90:91], v[90:91], v[102:103] op_sel_hi:[1,0]
	v_pk_mul_f32 v[84:85], v[84:85], v[102:103] op_sel_hi:[1,0]
	v_pk_mul_f32 v[86:87], v[86:87], v[102:103] op_sel_hi:[1,0]
	s_and_b64 vcc, exec, s[18:19]
	s_mov_b64 s[78:79], -1
	s_cbranch_vccnz .LBB0_288
	s_and_b64 vcc, exec, s[14:15]
	v_mov_b64_e32 v[102:103], v[96:97]
	v_mov_b64_e32 v[104:105], v[98:99]
	v_mov_b64_e32 v[106:107], v[92:93]
	v_mov_b64_e32 v[108:109], v[94:95]
	v_mov_b64_e32 v[110:111], v[88:89]
	v_mov_b64_e32 v[112:113], v[90:91]
	v_mov_b64_e32 v[114:115], v[84:85]
	v_mov_b64_e32 v[116:117], v[86:87]
	s_cbranch_vccnz .LBB0_287
	v_mul_f32_e32 v101, 0x3d922279, v96
	v_fmaak_f32 v101, v96, v101, 0x3fcc422a
	v_mul_f32_e32 v102, 0x3d922279, v97
	v_mul_f32_e32 v101, v96, v101
	v_fmaak_f32 v102, v97, v102, 0x3fcc422a
	v_mul_f32_e32 v101, 0xbfb8aa3b, v101
	v_mul_f32_e32 v102, v97, v102
	v_exp_f32_e32 v101, v101
	v_mul_f32_e32 v102, 0xbfb8aa3b, v102
	v_exp_f32_e32 v103, v102
	v_mul_f32_e32 v104, 0x3d922279, v99
	v_add_f32_e32 v101, 1.0, v101
	v_rcp_f32_e32 v102, v101
	v_add_f32_e32 v101, 1.0, v103
	v_rcp_f32_e32 v103, v101
	v_mul_f32_e32 v101, 0x3d922279, v98
	v_fmaak_f32 v101, v98, v101, 0x3fcc422a
	v_mul_f32_e32 v101, v98, v101
	v_fmaak_f32 v104, v99, v104, 0x3fcc422a
	v_mul_f32_e32 v101, 0xbfb8aa3b, v101
	v_mul_f32_e32 v104, v99, v104
	v_exp_f32_e32 v101, v101
	v_mul_f32_e32 v104, 0xbfb8aa3b, v104
	v_exp_f32_e32 v105, v104
	v_mul_f32_e32 v106, 0x3d922279, v93
	v_add_f32_e32 v101, 1.0, v101
	v_rcp_f32_e32 v104, v101
	v_add_f32_e32 v101, 1.0, v105
	v_rcp_f32_e32 v105, v101
	v_mul_f32_e32 v101, 0x3d922279, v92
	v_fmaak_f32 v101, v92, v101, 0x3fcc422a
	v_mul_f32_e32 v101, v92, v101
	v_fmaak_f32 v106, v93, v106, 0x3fcc422a
	v_mul_f32_e32 v101, 0xbfb8aa3b, v101
	v_mul_f32_e32 v106, v93, v106
	v_exp_f32_e32 v101, v101
	v_mul_f32_e32 v106, 0xbfb8aa3b, v106
	v_exp_f32_e32 v107, v106
	v_mul_f32_e32 v108, 0x3d922279, v95
	v_add_f32_e32 v101, 1.0, v101
	v_rcp_f32_e32 v106, v101
	v_add_f32_e32 v101, 1.0, v107
	v_rcp_f32_e32 v107, v101
	v_mul_f32_e32 v101, 0x3d922279, v94
	v_fmaak_f32 v101, v94, v101, 0x3fcc422a
	v_mul_f32_e32 v101, v94, v101
	v_fmaak_f32 v108, v95, v108, 0x3fcc422a
	v_mul_f32_e32 v101, 0xbfb8aa3b, v101
	v_mul_f32_e32 v108, v95, v108
	v_exp_f32_e32 v101, v101
	v_mul_f32_e32 v108, 0xbfb8aa3b, v108
	v_exp_f32_e32 v109, v108
	v_mul_f32_e32 v110, 0x3d922279, v89
	v_add_f32_e32 v101, 1.0, v101
	v_rcp_f32_e32 v108, v101
	v_add_f32_e32 v101, 1.0, v109
	v_rcp_f32_e32 v109, v101
	v_mul_f32_e32 v101, 0x3d922279, v88
	v_fmaak_f32 v101, v88, v101, 0x3fcc422a
	v_mul_f32_e32 v101, v88, v101
	v_fmaak_f32 v110, v89, v110, 0x3fcc422a
	v_mul_f32_e32 v101, 0xbfb8aa3b, v101
	v_mul_f32_e32 v110, v89, v110
	v_exp_f32_e32 v101, v101
	v_mul_f32_e32 v110, 0xbfb8aa3b, v110
	v_exp_f32_e32 v111, v110
	v_mul_f32_e32 v112, 0x3d922279, v91
	v_add_f32_e32 v101, 1.0, v101
	v_rcp_f32_e32 v110, v101
	v_add_f32_e32 v101, 1.0, v111
	v_rcp_f32_e32 v111, v101
	v_mul_f32_e32 v101, 0x3d922279, v90
	v_fmaak_f32 v101, v90, v101, 0x3fcc422a
	v_mul_f32_e32 v101, v90, v101
	v_fmaak_f32 v112, v91, v112, 0x3fcc422a
	v_mul_f32_e32 v101, 0xbfb8aa3b, v101
	v_mul_f32_e32 v112, v91, v112
	v_exp_f32_e32 v101, v101
	v_mul_f32_e32 v112, 0xbfb8aa3b, v112
	v_exp_f32_e32 v113, v112
	v_mul_f32_e32 v114, 0x3d922279, v85
	v_add_f32_e32 v101, 1.0, v101
	v_rcp_f32_e32 v112, v101
	v_add_f32_e32 v101, 1.0, v113
	v_rcp_f32_e32 v113, v101
	v_mul_f32_e32 v101, 0x3d922279, v84
	v_fmaak_f32 v101, v84, v101, 0x3fcc422a
	v_mul_f32_e32 v101, v84, v101
	v_fmaak_f32 v114, v85, v114, 0x3fcc422a
	v_mul_f32_e32 v101, 0xbfb8aa3b, v101
	v_mul_f32_e32 v114, v85, v114
	v_exp_f32_e32 v101, v101
	v_mul_f32_e32 v114, 0xbfb8aa3b, v114
	v_exp_f32_e32 v115, v114
	v_mul_f32_e32 v116, 0x3d922279, v87
	v_add_f32_e32 v101, 1.0, v101
	v_rcp_f32_e32 v114, v101
	v_add_f32_e32 v101, 1.0, v115
	v_rcp_f32_e32 v115, v101
	v_mul_f32_e32 v101, 0x3d922279, v86
	v_fmaak_f32 v101, v86, v101, 0x3fcc422a
	v_mul_f32_e32 v101, v86, v101
	v_fmaak_f32 v116, v87, v116, 0x3fcc422a
	v_mul_f32_e32 v101, 0xbfb8aa3b, v101
	v_mul_f32_e32 v116, v87, v116
	v_exp_f32_e32 v101, v101
	v_mul_f32_e32 v116, 0xbfb8aa3b, v116
	v_exp_f32_e32 v117, v116
	v_pk_mul_f32 v[102:103], v[96:97], v[102:103]
	v_add_f32_e32 v101, 1.0, v101
	v_rcp_f32_e32 v116, v101
	v_add_f32_e32 v101, 1.0, v117
	v_rcp_f32_e32 v117, v101
	v_pk_mul_f32 v[104:105], v[98:99], v[104:105]
	v_pk_mul_f32 v[106:107], v[92:93], v[106:107]
	v_pk_mul_f32 v[108:109], v[94:95], v[108:109]
	v_pk_mul_f32 v[110:111], v[88:89], v[110:111]
	v_pk_mul_f32 v[112:113], v[90:91], v[112:113]
	v_pk_mul_f32 v[114:115], v[84:85], v[114:115]
	s_andn2_b64 vcc, exec, s[76:77]
	v_pk_mul_f32 v[116:117], v[86:87], v[116:117]
	s_cbranch_vccnz .LBB0_287
	v_pk_mul_f32 v[118:119], v[102:103], v[102:103]
	v_pk_mul_f32 v[120:121], v[104:105], v[104:105]
	v_add_f32_e32 v101, v118, v119
	v_add_f32_e32 v101, v120, v101
	v_pk_mul_f32 v[122:123], v[106:107], v[106:107]
	v_add_f32_e32 v101, v121, v101
	v_add_f32_e32 v101, v122, v101
	v_pk_mul_f32 v[124:125], v[108:109], v[108:109]
	v_add_f32_e32 v101, v123, v101
	v_add_f32_e32 v101, v124, v101
	v_pk_mul_f32 v[126:127], v[110:111], v[110:111]
	v_add_f32_e32 v101, v125, v101
	v_add_f32_e32 v101, v126, v101
	v_pk_mul_f32 v[128:129], v[112:113], v[112:113]
	v_add_f32_e32 v101, v127, v101
	v_add_f32_e32 v101, v128, v101
	v_mbcnt_hi_u32_b32 v119, -1, v1
	v_pk_mul_f32 v[130:131], v[114:115], v[114:115]
	v_add_f32_e32 v101, v129, v101
	v_and_b32_e32 v120, 64, v119
	v_add_f32_e32 v101, v130, v101
	v_xor_b32_e32 v118, 16, v119
	v_add_u32_e32 v120, 64, v120
	v_pk_mul_f32 v[134:135], v[116:117], v[116:117]
	v_add_f32_e32 v101, v131, v101
	v_cmp_lt_i32_e32 vcc, v118, v120
	v_add_f32_e32 v101, v134, v101
	v_add_f32_e32 v101, v135, v101
	v_cndmask_b32_e32 v118, v119, v118, vcc
	v_lshlrev_b32_e32 v118, 2, v118
	v_mov_b32_e32 v118, v101
	s_nop 1
	v_permlane16_swap_b32_e32 v118, v101
	s_waitcnt lgkmcnt(0)
	v_add_f32_e32 v118, v101, v118
	v_xor_b32_e32 v101, 32, v119
	v_cmp_lt_i32_e32 vcc, v101, v120
	s_nop 1
	v_cndmask_b32_e32 v101, v119, v101, vcc
	v_lshlrev_b32_e32 v101, 2, v101
	v_mov_b32_e32 v119, v118
	s_nop 1
	v_permlane32_swap_b32_e32 v119, v118
	s_and_saveexec_b64 s[78:79], s[10:11]
	s_cbranch_execz .LBB0_286
	v_ashrrev_i32_e32 v101, 31, v100
	v_lshlrev_b64 v[120:121], 5, v[100:101]
	v_lshl_add_u64 v[120:121], s[64:65], 0, v[120:121]
	s_lshl_b32 s24, s69, 2
	v_lshl_add_u64 v[120:121], v[120:121], 0, s[24:25]
	s_lshl_b32 s24, s21, 2
	v_lshl_add_u64 v[120:121], v[120:121], 0, s[24:25]
	s_waitcnt lgkmcnt(0)
	v_add_f32_e32 v101, v118, v119
	global_store_dword v[120:121], v101, off

.LBB0_288:
	s_andn2_b64 vcc, exec, s[78:79]
	s_cbranch_vccnz .LBB0_290
	v_pk_mul_f32 v[102:103], v[96:97], v[96:97]
	v_pk_mul_f32 v[104:105], v[98:99], v[98:99]
	v_add_f32_e32 v101, v102, v103
	v_add_f32_e32 v101, v104, v101
	v_pk_mul_f32 v[106:107], v[92:93], v[92:93]
	v_add_f32_e32 v101, v105, v101
	v_add_f32_e32 v101, v106, v101
	v_pk_mul_f32 v[108:109], v[94:95], v[94:95]
	v_add_f32_e32 v101, v107, v101
	v_add_f32_e32 v101, v108, v101
	v_pk_mul_f32 v[110:111], v[88:89], v[88:89]
	v_add_f32_e32 v101, v109, v101
	v_add_f32_e32 v101, v110, v101
	v_pk_mul_f32 v[112:113], v[90:91], v[90:91]
	v_add_f32_e32 v101, v111, v101
	v_add_f32_e32 v101, v112, v101
	v_mbcnt_hi_u32_b32 v102, -1, v1
	v_pk_mul_f32 v[114:115], v[84:85], v[84:85]
	v_add_f32_e32 v101, v113, v101
	v_and_b32_e32 v104, 64, v102
	v_add_f32_e32 v101, v114, v101
	v_xor_b32_e32 v103, 16, v102
	v_add_u32_e32 v104, 64, v104
	v_pk_mul_f32 v[116:117], v[86:87], v[86:87]
	v_add_f32_e32 v101, v115, v101
	v_cmp_lt_i32_e32 vcc, v103, v104
	v_add_f32_e32 v101, v116, v101
	v_add_f32_e32 v101, v117, v101
	v_cndmask_b32_e32 v103, v102, v103, vcc
	v_lshlrev_b32_e32 v103, 2, v103
	v_mov_b32_e32 v103, v101
	s_nop 1
	v_permlane16_swap_b32_e32 v103, v101
	s_waitcnt lgkmcnt(0)
	v_add_f32_e32 v101, v101, v103
	v_xor_b32_e32 v103, 32, v102
	v_cmp_lt_i32_e32 vcc, v103, v104
	s_nop 1
	v_cndmask_b32_e32 v102, v102, v103, vcc
	v_lshlrev_b32_e32 v102, 2, v102
	v_mov_b32_e32 v102, v101
	s_nop 1
	v_permlane32_swap_b32_e32 v102, v101
	s_waitcnt lgkmcnt(0)
	v_add_f32_e32 v101, v101, v102
	v_fmamk_f32 v101, v101, 0x3c800000, v193
	v_rsq_f32_e32 v116, v101
	s_nop 0
	v_pk_mul_f32 v[96:97], v[96:97], v[116:117] op_sel_hi:[1,0]
	v_pk_mul_f32 v[92:93], v[92:93], v[116:117] op_sel_hi:[1,0]
	v_pk_mul_f32 v[88:89], v[88:89], v[116:117] op_sel_hi:[1,0]
	v_pk_mul_f32 v[84:85], v[84:85], v[116:117] op_sel_hi:[1,0]
	v_pk_mul_f32 v[102:103], v[36:37], v[96:97]
	v_pk_mul_f32 v[96:97], v[98:99], v[116:117] op_sel_hi:[1,0]
	v_pk_mul_f32 v[106:107], v[24:25], v[92:93]
	v_pk_mul_f32 v[92:93], v[94:95], v[116:117] op_sel_hi:[1,0]
	v_pk_mul_f32 v[110:111], v[28:29], v[88:89]
	v_pk_mul_f32 v[88:89], v[90:91], v[116:117] op_sel_hi:[1,0]
	v_pk_mul_f32 v[114:115], v[20:21], v[84:85]
	v_pk_mul_f32 v[84:85], v[86:87], v[116:117] op_sel_hi:[1,0]
	v_pk_mul_f32 v[104:105], v[38:39], v[96:97]
	v_pk_mul_f32 v[108:109], v[26:27], v[92:93]
	v_pk_mul_f32 v[112:113], v[30:31], v[88:89]
	v_pk_mul_f32 v[116:117], v[22:23], v[84:85]

.LBB0_294:
	s_waitcnt lgkmcnt(0)
	v_pk_mul_f32 v[80:81], v[80:81], v[86:87] op_sel_hi:[1,0]
	v_pk_mul_f32 v[82:83], v[82:83], v[86:87] op_sel_hi:[1,0]
	v_pk_mul_f32 v[76:77], v[76:77], v[86:87] op_sel_hi:[1,0]
	v_pk_mul_f32 v[78:79], v[78:79], v[86:87] op_sel_hi:[1,0]
	v_pk_mul_f32 v[72:73], v[72:73], v[86:87] op_sel_hi:[1,0]
	v_pk_mul_f32 v[74:75], v[74:75], v[86:87] op_sel_hi:[1,0]
	v_pk_mul_f32 v[68:69], v[68:69], v[86:87] op_sel_hi:[1,0]
	v_pk_mul_f32 v[70:71], v[70:71], v[86:87] op_sel_hi:[1,0]
	s_and_b64 vcc, exec, s[18:19]
	s_mov_b64 s[78:79], -1
	s_cbranch_vccnz .LBB0_301
	s_and_b64 vcc, exec, s[14:15]
	v_mov_b64_e32 v[86:87], v[80:81]
	v_mov_b64_e32 v[88:89], v[82:83]
	v_mov_b64_e32 v[90:91], v[76:77]
	v_mov_b64_e32 v[92:93], v[78:79]
	v_mov_b64_e32 v[94:95], v[72:73]
	v_mov_b64_e32 v[96:97], v[74:75]
	v_mov_b64_e32 v[98:99], v[68:69]
	v_mov_b64_e32 v[100:101], v[70:71]
	s_cbranch_vccnz .LBB0_300
	v_mul_f32_e32 v85, 0x3d922279, v80
	v_fmaak_f32 v85, v80, v85, 0x3fcc422a
	v_mul_f32_e32 v86, 0x3d922279, v81
	v_mul_f32_e32 v85, v80, v85
	v_fmaak_f32 v86, v81, v86, 0x3fcc422a
	v_mul_f32_e32 v85, 0xbfb8aa3b, v85
	v_mul_f32_e32 v86, v81, v86
	v_exp_f32_e32 v85, v85
	v_mul_f32_e32 v86, 0xbfb8aa3b, v86
	v_exp_f32_e32 v87, v86
	v_mul_f32_e32 v88, 0x3d922279, v83
	v_add_f32_e32 v85, 1.0, v85
	v_rcp_f32_e32 v86, v85
	v_add_f32_e32 v85, 1.0, v87
	v_rcp_f32_e32 v87, v85
	v_mul_f32_e32 v85, 0x3d922279, v82
	v_fmaak_f32 v85, v82, v85, 0x3fcc422a
	v_mul_f32_e32 v85, v82, v85
	v_fmaak_f32 v88, v83, v88, 0x3fcc422a
	v_mul_f32_e32 v85, 0xbfb8aa3b, v85
	v_mul_f32_e32 v88, v83, v88
	v_exp_f32_e32 v85, v85
	v_mul_f32_e32 v88, 0xbfb8aa3b, v88
	v_exp_f32_e32 v89, v88
	v_mul_f32_e32 v90, 0x3d922279, v77
	v_add_f32_e32 v85, 1.0, v85
	v_rcp_f32_e32 v88, v85
	v_add_f32_e32 v85, 1.0, v89
	v_rcp_f32_e32 v89, v85
	v_mul_f32_e32 v85, 0x3d922279, v76
	v_fmaak_f32 v85, v76, v85, 0x3fcc422a
	v_mul_f32_e32 v85, v76, v85
	v_fmaak_f32 v90, v77, v90, 0x3fcc422a
	v_mul_f32_e32 v85, 0xbfb8aa3b, v85
	v_mul_f32_e32 v90, v77, v90
	v_exp_f32_e32 v85, v85
	v_mul_f32_e32 v90, 0xbfb8aa3b, v90
	v_exp_f32_e32 v91, v90
	v_mul_f32_e32 v92, 0x3d922279, v79
	v_add_f32_e32 v85, 1.0, v85
	v_rcp_f32_e32 v90, v85
	v_add_f32_e32 v85, 1.0, v91
	v_rcp_f32_e32 v91, v85
	v_mul_f32_e32 v85, 0x3d922279, v78
	v_fmaak_f32 v85, v78, v85, 0x3fcc422a
	v_mul_f32_e32 v85, v78, v85
	v_fmaak_f32 v92, v79, v92, 0x3fcc422a
	v_mul_f32_e32 v85, 0xbfb8aa3b, v85
	v_mul_f32_e32 v92, v79, v92
	v_exp_f32_e32 v85, v85
	v_mul_f32_e32 v92, 0xbfb8aa3b, v92
	v_exp_f32_e32 v93, v92
	v_mul_f32_e32 v94, 0x3d922279, v73
	v_add_f32_e32 v85, 1.0, v85
	v_rcp_f32_e32 v92, v85
	v_add_f32_e32 v85, 1.0, v93
	v_rcp_f32_e32 v93, v85
	v_mul_f32_e32 v85, 0x3d922279, v72
	v_fmaak_f32 v85, v72, v85, 0x3fcc422a
	v_mul_f32_e32 v85, v72, v85
	v_fmaak_f32 v94, v73, v94, 0x3fcc422a
	v_mul_f32_e32 v85, 0xbfb8aa3b, v85
	v_mul_f32_e32 v94, v73, v94
	v_exp_f32_e32 v85, v85
	v_mul_f32_e32 v94, 0xbfb8aa3b, v94
	v_exp_f32_e32 v95, v94
	v_mul_f32_e32 v96, 0x3d922279, v75
	v_add_f32_e32 v85, 1.0, v85
	v_rcp_f32_e32 v94, v85
	v_add_f32_e32 v85, 1.0, v95
	v_rcp_f32_e32 v95, v85
	v_mul_f32_e32 v85, 0x3d922279, v74
	v_fmaak_f32 v85, v74, v85, 0x3fcc422a
	v_mul_f32_e32 v85, v74, v85
	v_fmaak_f32 v96, v75, v96, 0x3fcc422a
	v_mul_f32_e32 v85, 0xbfb8aa3b, v85
	v_mul_f32_e32 v96, v75, v96
	v_exp_f32_e32 v85, v85
	v_mul_f32_e32 v96, 0xbfb8aa3b, v96
	v_exp_f32_e32 v97, v96
	v_mul_f32_e32 v98, 0x3d922279, v69
	v_add_f32_e32 v85, 1.0, v85
	v_rcp_f32_e32 v96, v85
	v_add_f32_e32 v85, 1.0, v97
	v_rcp_f32_e32 v97, v85
	v_mul_f32_e32 v85, 0x3d922279, v68
	v_fmaak_f32 v85, v68, v85, 0x3fcc422a
	v_mul_f32_e32 v85, v68, v85
	v_fmaak_f32 v98, v69, v98, 0x3fcc422a
	v_mul_f32_e32 v85, 0xbfb8aa3b, v85
	v_mul_f32_e32 v98, v69, v98
	v_exp_f32_e32 v85, v85
	v_mul_f32_e32 v98, 0xbfb8aa3b, v98
	v_exp_f32_e32 v99, v98
	v_mul_f32_e32 v100, 0x3d922279, v71
	v_add_f32_e32 v85, 1.0, v85
	v_rcp_f32_e32 v98, v85
	v_add_f32_e32 v85, 1.0, v99
	v_rcp_f32_e32 v99, v85
	v_mul_f32_e32 v85, 0x3d922279, v70
	v_fmaak_f32 v85, v70, v85, 0x3fcc422a
	v_mul_f32_e32 v85, v70, v85
	v_fmaak_f32 v100, v71, v100, 0x3fcc422a
	v_mul_f32_e32 v85, 0xbfb8aa3b, v85
	v_mul_f32_e32 v100, v71, v100
	v_exp_f32_e32 v85, v85
	v_mul_f32_e32 v100, 0xbfb8aa3b, v100
	v_exp_f32_e32 v101, v100
	v_pk_mul_f32 v[86:87], v[80:81], v[86:87]
	v_add_f32_e32 v85, 1.0, v85
	v_rcp_f32_e32 v100, v85
	v_add_f32_e32 v85, 1.0, v101
	v_rcp_f32_e32 v101, v85
	v_pk_mul_f32 v[88:89], v[82:83], v[88:89]
	v_pk_mul_f32 v[90:91], v[76:77], v[90:91]
	v_pk_mul_f32 v[92:93], v[78:79], v[92:93]
	v_pk_mul_f32 v[94:95], v[72:73], v[94:95]
	v_pk_mul_f32 v[96:97], v[74:75], v[96:97]
	v_pk_mul_f32 v[98:99], v[68:69], v[98:99]
	s_andn2_b64 vcc, exec, s[76:77]
	v_pk_mul_f32 v[100:101], v[70:71], v[100:101]
	s_cbranch_vccnz .LBB0_300
	v_pk_mul_f32 v[102:103], v[86:87], v[86:87]
	v_pk_mul_f32 v[104:105], v[88:89], v[88:89]
	v_add_f32_e32 v85, v102, v103
	v_add_f32_e32 v85, v104, v85
	v_pk_mul_f32 v[106:107], v[90:91], v[90:91]
	v_add_f32_e32 v85, v105, v85
	v_add_f32_e32 v85, v106, v85
	v_pk_mul_f32 v[108:109], v[92:93], v[92:93]
	v_add_f32_e32 v85, v107, v85
	v_add_f32_e32 v85, v108, v85
	v_pk_mul_f32 v[110:111], v[94:95], v[94:95]
	v_add_f32_e32 v85, v109, v85
	v_add_f32_e32 v85, v110, v85
	v_pk_mul_f32 v[112:113], v[96:97], v[96:97]
	v_add_f32_e32 v85, v111, v85
	v_add_f32_e32 v85, v112, v85
	v_mbcnt_hi_u32_b32 v103, -1, v1
	v_pk_mul_f32 v[114:115], v[98:99], v[98:99]
	v_add_f32_e32 v85, v113, v85
	v_and_b32_e32 v104, 64, v103
	v_add_f32_e32 v85, v114, v85
	v_xor_b32_e32 v102, 16, v103
	v_add_u32_e32 v104, 64, v104
	v_pk_mul_f32 v[116:117], v[100:101], v[100:101]
	v_add_f32_e32 v85, v115, v85
	v_cmp_lt_i32_e32 vcc, v102, v104
	v_add_f32_e32 v85, v116, v85
	v_add_f32_e32 v85, v117, v85
	v_cndmask_b32_e32 v102, v103, v102, vcc
	v_lshlrev_b32_e32 v102, 2, v102
	v_mov_b32_e32 v102, v85
	s_nop 1
	v_permlane16_swap_b32_e32 v102, v85
	s_waitcnt lgkmcnt(0)
	v_add_f32_e32 v102, v85, v102
	v_xor_b32_e32 v85, 32, v103
	v_cmp_lt_i32_e32 vcc, v85, v104
	s_nop 1
	v_cndmask_b32_e32 v85, v103, v85, vcc
	v_lshlrev_b32_e32 v85, 2, v85
	v_mov_b32_e32 v103, v102
	s_nop 1
	v_permlane32_swap_b32_e32 v103, v102
	s_and_saveexec_b64 s[78:79], s[10:11]
	s_cbranch_execz .LBB0_299
	v_ashrrev_i32_e32 v85, 31, v84
	v_lshlrev_b64 v[104:105], 5, v[84:85]
	v_lshl_add_u64 v[104:105], s[64:65], 0, v[104:105]
	s_lshl_b32 s24, s69, 2
	v_lshl_add_u64 v[104:105], v[104:105], 0, s[24:25]
	s_lshl_b32 s24, s21, 2
	v_lshl_add_u64 v[104:105], v[104:105], 0, s[24:25]
	s_waitcnt lgkmcnt(0)
	v_add_f32_e32 v85, v102, v103
	global_store_dword v[104:105], v85, off

.LBB0_301:
	s_andn2_b64 vcc, exec, s[78:79]
	s_cbranch_vccnz .LBB0_303
	v_pk_mul_f32 v[86:87], v[80:81], v[80:81]
	v_pk_mul_f32 v[88:89], v[82:83], v[82:83]
	v_add_f32_e32 v85, v86, v87
	v_add_f32_e32 v85, v88, v85
	v_pk_mul_f32 v[90:91], v[76:77], v[76:77]
	v_add_f32_e32 v85, v89, v85
	v_add_f32_e32 v85, v90, v85
	v_pk_mul_f32 v[92:93], v[78:79], v[78:79]
	v_add_f32_e32 v85, v91, v85
	v_add_f32_e32 v85, v92, v85
	v_pk_mul_f32 v[94:95], v[72:73], v[72:73]
	v_add_f32_e32 v85, v93, v85
	v_add_f32_e32 v85, v94, v85
	v_pk_mul_f32 v[96:97], v[74:75], v[74:75]
	v_add_f32_e32 v85, v95, v85
	v_add_f32_e32 v85, v96, v85
	v_mbcnt_hi_u32_b32 v86, -1, v1
	v_pk_mul_f32 v[98:99], v[68:69], v[68:69]
	v_add_f32_e32 v85, v97, v85
	v_and_b32_e32 v88, 64, v86
	v_add_f32_e32 v85, v98, v85
	v_xor_b32_e32 v87, 16, v86
	v_add_u32_e32 v88, 64, v88
	v_pk_mul_f32 v[100:101], v[70:71], v[70:71]
	v_add_f32_e32 v85, v99, v85
	v_cmp_lt_i32_e32 vcc, v87, v88
	v_add_f32_e32 v85, v100, v85
	v_add_f32_e32 v85, v101, v85
	v_cndmask_b32_e32 v87, v86, v87, vcc
	v_lshlrev_b32_e32 v87, 2, v87
	v_mov_b32_e32 v87, v85
	s_nop 1
	v_permlane16_swap_b32_e32 v87, v85
	s_waitcnt lgkmcnt(0)
	v_add_f32_e32 v85, v85, v87
	v_xor_b32_e32 v87, 32, v86
	v_cmp_lt_i32_e32 vcc, v87, v88
	s_nop 1
	v_cndmask_b32_e32 v86, v86, v87, vcc
	v_lshlrev_b32_e32 v86, 2, v86
	v_mov_b32_e32 v86, v85
	s_nop 1
	v_permlane32_swap_b32_e32 v86, v85
	s_waitcnt lgkmcnt(0)
	v_add_f32_e32 v85, v85, v86
	v_fmamk_f32 v85, v85, 0x3c800000, v193
	v_rsq_f32_e32 v100, v85
	s_nop 0
	v_pk_mul_f32 v[80:81], v[80:81], v[100:101] op_sel_hi:[1,0]
	v_pk_mul_f32 v[76:77], v[76:77], v[100:101] op_sel_hi:[1,0]
	v_pk_mul_f32 v[72:73], v[72:73], v[100:101] op_sel_hi:[1,0]
	v_pk_mul_f32 v[68:69], v[68:69], v[100:101] op_sel_hi:[1,0]
	v_pk_mul_f32 v[86:87], v[36:37], v[80:81]
	v_pk_mul_f32 v[80:81], v[82:83], v[100:101] op_sel_hi:[1,0]
	v_pk_mul_f32 v[90:91], v[24:25], v[76:77]
	v_pk_mul_f32 v[76:77], v[78:79], v[100:101] op_sel_hi:[1,0]
	v_pk_mul_f32 v[94:95], v[28:29], v[72:73]
	v_pk_mul_f32 v[72:73], v[74:75], v[100:101] op_sel_hi:[1,0]
	v_pk_mul_f32 v[98:99], v[20:21], v[68:69]
	v_pk_mul_f32 v[68:69], v[70:71], v[100:101] op_sel_hi:[1,0]
	v_pk_mul_f32 v[88:89], v[38:39], v[80:81]
	v_pk_mul_f32 v[92:93], v[26:27], v[76:77]
	v_pk_mul_f32 v[96:97], v[30:31], v[72:73]
	v_pk_mul_f32 v[100:101], v[22:23], v[68:69]

.LBB0_307:
	s_waitcnt lgkmcnt(0)
	v_pk_mul_f32 v[64:65], v[64:65], v[70:71] op_sel_hi:[1,0]
	v_pk_mul_f32 v[66:67], v[66:67], v[70:71] op_sel_hi:[1,0]
	v_pk_mul_f32 v[60:61], v[60:61], v[70:71] op_sel_hi:[1,0]
	v_pk_mul_f32 v[62:63], v[62:63], v[70:71] op_sel_hi:[1,0]
	v_pk_mul_f32 v[56:57], v[56:57], v[70:71] op_sel_hi:[1,0]
	v_pk_mul_f32 v[58:59], v[58:59], v[70:71] op_sel_hi:[1,0]
	v_pk_mul_f32 v[52:53], v[52:53], v[70:71] op_sel_hi:[1,0]
	v_pk_mul_f32 v[54:55], v[54:55], v[70:71] op_sel_hi:[1,0]
	s_and_b64 vcc, exec, s[18:19]
	s_mov_b64 s[78:79], -1
	s_cbranch_vccnz .LBB0_314
	s_and_b64 vcc, exec, s[14:15]
	v_mov_b64_e32 v[70:71], v[64:65]
	v_mov_b64_e32 v[72:73], v[66:67]
	v_mov_b64_e32 v[74:75], v[60:61]
	v_mov_b64_e32 v[76:77], v[62:63]
	v_mov_b64_e32 v[78:79], v[56:57]
	v_mov_b64_e32 v[80:81], v[58:59]
	v_mov_b64_e32 v[82:83], v[52:53]
	v_mov_b64_e32 v[84:85], v[54:55]
	s_cbranch_vccnz .LBB0_313
	v_mul_f32_e32 v69, 0x3d922279, v64
	v_fmaak_f32 v69, v64, v69, 0x3fcc422a
	v_mul_f32_e32 v70, 0x3d922279, v65
	v_mul_f32_e32 v69, v64, v69
	v_fmaak_f32 v70, v65, v70, 0x3fcc422a
	v_mul_f32_e32 v69, 0xbfb8aa3b, v69
	v_mul_f32_e32 v70, v65, v70
	v_exp_f32_e32 v69, v69
	v_mul_f32_e32 v70, 0xbfb8aa3b, v70
	v_exp_f32_e32 v71, v70
	v_mul_f32_e32 v72, 0x3d922279, v67
	v_add_f32_e32 v69, 1.0, v69
	v_rcp_f32_e32 v70, v69
	v_add_f32_e32 v69, 1.0, v71
	v_rcp_f32_e32 v71, v69
	v_mul_f32_e32 v69, 0x3d922279, v66
	v_fmaak_f32 v69, v66, v69, 0x3fcc422a
	v_mul_f32_e32 v69, v66, v69
	v_fmaak_f32 v72, v67, v72, 0x3fcc422a
	v_mul_f32_e32 v69, 0xbfb8aa3b, v69
	v_mul_f32_e32 v72, v67, v72
	v_exp_f32_e32 v69, v69
	v_mul_f32_e32 v72, 0xbfb8aa3b, v72
	v_exp_f32_e32 v73, v72
	v_mul_f32_e32 v74, 0x3d922279, v61
	v_add_f32_e32 v69, 1.0, v69
	v_rcp_f32_e32 v72, v69
	v_add_f32_e32 v69, 1.0, v73
	v_rcp_f32_e32 v73, v69
	v_mul_f32_e32 v69, 0x3d922279, v60
	v_fmaak_f32 v69, v60, v69, 0x3fcc422a
	v_mul_f32_e32 v69, v60, v69
	v_fmaak_f32 v74, v61, v74, 0x3fcc422a
	v_mul_f32_e32 v69, 0xbfb8aa3b, v69
	v_mul_f32_e32 v74, v61, v74
	v_exp_f32_e32 v69, v69
	v_mul_f32_e32 v74, 0xbfb8aa3b, v74
	v_exp_f32_e32 v75, v74
	v_mul_f32_e32 v76, 0x3d922279, v63
	v_add_f32_e32 v69, 1.0, v69
	v_rcp_f32_e32 v74, v69
	v_add_f32_e32 v69, 1.0, v75
	v_rcp_f32_e32 v75, v69
	v_mul_f32_e32 v69, 0x3d922279, v62
	v_fmaak_f32 v69, v62, v69, 0x3fcc422a
	v_mul_f32_e32 v69, v62, v69
	v_fmaak_f32 v76, v63, v76, 0x3fcc422a
	v_mul_f32_e32 v69, 0xbfb8aa3b, v69
	v_mul_f32_e32 v76, v63, v76
	v_exp_f32_e32 v69, v69
	v_mul_f32_e32 v76, 0xbfb8aa3b, v76
	v_exp_f32_e32 v77, v76
	v_mul_f32_e32 v78, 0x3d922279, v57
	v_add_f32_e32 v69, 1.0, v69
	v_rcp_f32_e32 v76, v69
	v_add_f32_e32 v69, 1.0, v77
	v_rcp_f32_e32 v77, v69
	v_mul_f32_e32 v69, 0x3d922279, v56
	v_fmaak_f32 v69, v56, v69, 0x3fcc422a
	v_mul_f32_e32 v69, v56, v69
	v_fmaak_f32 v78, v57, v78, 0x3fcc422a
	v_mul_f32_e32 v69, 0xbfb8aa3b, v69
	v_mul_f32_e32 v78, v57, v78
	v_exp_f32_e32 v69, v69
	v_mul_f32_e32 v78, 0xbfb8aa3b, v78
	v_exp_f32_e32 v79, v78
	v_mul_f32_e32 v80, 0x3d922279, v59
	v_add_f32_e32 v69, 1.0, v69
	v_rcp_f32_e32 v78, v69
	v_add_f32_e32 v69, 1.0, v79
	v_rcp_f32_e32 v79, v69
	v_mul_f32_e32 v69, 0x3d922279, v58
	v_fmaak_f32 v69, v58, v69, 0x3fcc422a
	v_mul_f32_e32 v69, v58, v69
	v_fmaak_f32 v80, v59, v80, 0x3fcc422a
	v_mul_f32_e32 v69, 0xbfb8aa3b, v69
	v_mul_f32_e32 v80, v59, v80
	v_exp_f32_e32 v69, v69
	v_mul_f32_e32 v80, 0xbfb8aa3b, v80
	v_exp_f32_e32 v81, v80
	v_mul_f32_e32 v82, 0x3d922279, v53
	v_add_f32_e32 v69, 1.0, v69
	v_rcp_f32_e32 v80, v69
	v_add_f32_e32 v69, 1.0, v81
	v_rcp_f32_e32 v81, v69
	v_mul_f32_e32 v69, 0x3d922279, v52
	v_fmaak_f32 v69, v52, v69, 0x3fcc422a
	v_mul_f32_e32 v69, v52, v69
	v_fmaak_f32 v82, v53, v82, 0x3fcc422a
	v_mul_f32_e32 v69, 0xbfb8aa3b, v69
	v_mul_f32_e32 v82, v53, v82
	v_exp_f32_e32 v69, v69
	v_mul_f32_e32 v82, 0xbfb8aa3b, v82
	v_exp_f32_e32 v83, v82
	v_mul_f32_e32 v84, 0x3d922279, v55
	v_add_f32_e32 v69, 1.0, v69
	v_rcp_f32_e32 v82, v69
	v_add_f32_e32 v69, 1.0, v83
	v_rcp_f32_e32 v83, v69
	v_mul_f32_e32 v69, 0x3d922279, v54
	v_fmaak_f32 v69, v54, v69, 0x3fcc422a
	v_mul_f32_e32 v69, v54, v69
	v_fmaak_f32 v84, v55, v84, 0x3fcc422a
	v_mul_f32_e32 v69, 0xbfb8aa3b, v69
	v_mul_f32_e32 v84, v55, v84
	v_exp_f32_e32 v69, v69
	v_mul_f32_e32 v84, 0xbfb8aa3b, v84
	v_exp_f32_e32 v85, v84
	v_pk_mul_f32 v[70:71], v[64:65], v[70:71]
	v_add_f32_e32 v69, 1.0, v69
	v_rcp_f32_e32 v84, v69
	v_add_f32_e32 v69, 1.0, v85
	v_rcp_f32_e32 v85, v69
	v_pk_mul_f32 v[72:73], v[66:67], v[72:73]
	v_pk_mul_f32 v[74:75], v[60:61], v[74:75]
	v_pk_mul_f32 v[76:77], v[62:63], v[76:77]
	v_pk_mul_f32 v[78:79], v[56:57], v[78:79]
	v_pk_mul_f32 v[80:81], v[58:59], v[80:81]
	v_pk_mul_f32 v[82:83], v[52:53], v[82:83]
	s_andn2_b64 vcc, exec, s[76:77]
	v_pk_mul_f32 v[84:85], v[54:55], v[84:85]
	s_cbranch_vccnz .LBB0_313
	v_pk_mul_f32 v[86:87], v[70:71], v[70:71]
	v_pk_mul_f32 v[88:89], v[72:73], v[72:73]
	v_add_f32_e32 v69, v86, v87
	v_add_f32_e32 v69, v88, v69
	v_pk_mul_f32 v[90:91], v[74:75], v[74:75]
	v_add_f32_e32 v69, v89, v69
	v_add_f32_e32 v69, v90, v69
	v_pk_mul_f32 v[92:93], v[76:77], v[76:77]
	v_add_f32_e32 v69, v91, v69
	v_add_f32_e32 v69, v92, v69
	v_pk_mul_f32 v[94:95], v[78:79], v[78:79]
	v_add_f32_e32 v69, v93, v69
	v_add_f32_e32 v69, v94, v69
	v_pk_mul_f32 v[96:97], v[80:81], v[80:81]
	v_add_f32_e32 v69, v95, v69
	v_add_f32_e32 v69, v96, v69
	v_mbcnt_hi_u32_b32 v87, -1, v1
	v_pk_mul_f32 v[98:99], v[82:83], v[82:83]
	v_add_f32_e32 v69, v97, v69
	v_and_b32_e32 v88, 64, v87
	v_add_f32_e32 v69, v98, v69
	v_xor_b32_e32 v86, 16, v87
	v_add_u32_e32 v88, 64, v88
	v_pk_mul_f32 v[100:101], v[84:85], v[84:85]
	v_add_f32_e32 v69, v99, v69
	v_cmp_lt_i32_e32 vcc, v86, v88
	v_add_f32_e32 v69, v100, v69
	v_add_f32_e32 v69, v101, v69
	v_cndmask_b32_e32 v86, v87, v86, vcc
	v_lshlrev_b32_e32 v86, 2, v86
	v_mov_b32_e32 v86, v69
	s_nop 1
	v_permlane16_swap_b32_e32 v86, v69
	s_waitcnt lgkmcnt(0)
	v_add_f32_e32 v86, v69, v86
	v_xor_b32_e32 v69, 32, v87
	v_cmp_lt_i32_e32 vcc, v69, v88
	s_nop 1
	v_cndmask_b32_e32 v69, v87, v69, vcc
	v_lshlrev_b32_e32 v69, 2, v69
	v_mov_b32_e32 v87, v86
	s_nop 1
	v_permlane32_swap_b32_e32 v87, v86
	s_and_saveexec_b64 s[78:79], s[10:11]
	s_cbranch_execz .LBB0_312
	v_ashrrev_i32_e32 v69, 31, v68
	v_lshlrev_b64 v[88:89], 5, v[68:69]
	v_lshl_add_u64 v[88:89], s[64:65], 0, v[88:89]
	s_lshl_b32 s24, s69, 2
	v_lshl_add_u64 v[88:89], v[88:89], 0, s[24:25]
	s_lshl_b32 s24, s21, 2
	v_lshl_add_u64 v[88:89], v[88:89], 0, s[24:25]
	s_waitcnt lgkmcnt(0)
	v_add_f32_e32 v69, v86, v87
	global_store_dword v[88:89], v69, off

.LBB0_314:
	s_andn2_b64 vcc, exec, s[78:79]
	s_cbranch_vccnz .LBB0_316
	v_pk_mul_f32 v[70:71], v[64:65], v[64:65]
	v_pk_mul_f32 v[72:73], v[66:67], v[66:67]
	v_add_f32_e32 v69, v70, v71
	v_add_f32_e32 v69, v72, v69
	v_pk_mul_f32 v[74:75], v[60:61], v[60:61]
	v_add_f32_e32 v69, v73, v69
	v_add_f32_e32 v69, v74, v69
	v_pk_mul_f32 v[76:77], v[62:63], v[62:63]
	v_add_f32_e32 v69, v75, v69
	v_add_f32_e32 v69, v76, v69
	v_pk_mul_f32 v[78:79], v[56:57], v[56:57]
	v_add_f32_e32 v69, v77, v69
	v_add_f32_e32 v69, v78, v69
	v_pk_mul_f32 v[80:81], v[58:59], v[58:59]
	v_add_f32_e32 v69, v79, v69
	v_add_f32_e32 v69, v80, v69
	v_mbcnt_hi_u32_b32 v70, -1, v1
	v_pk_mul_f32 v[82:83], v[52:53], v[52:53]
	v_add_f32_e32 v69, v81, v69
	v_and_b32_e32 v72, 64, v70
	v_add_f32_e32 v69, v82, v69
	v_xor_b32_e32 v71, 16, v70
	v_add_u32_e32 v72, 64, v72
	v_pk_mul_f32 v[84:85], v[54:55], v[54:55]
	v_add_f32_e32 v69, v83, v69
	v_cmp_lt_i32_e32 vcc, v71, v72
	v_add_f32_e32 v69, v84, v69
	v_add_f32_e32 v69, v85, v69
	v_cndmask_b32_e32 v71, v70, v71, vcc
	v_lshlrev_b32_e32 v71, 2, v71
	v_mov_b32_e32 v71, v69
	s_nop 1
	v_permlane16_swap_b32_e32 v71, v69
	s_waitcnt lgkmcnt(0)
	v_add_f32_e32 v69, v69, v71
	v_xor_b32_e32 v71, 32, v70
	v_cmp_lt_i32_e32 vcc, v71, v72
	s_nop 1
	v_cndmask_b32_e32 v70, v70, v71, vcc
	v_lshlrev_b32_e32 v70, 2, v70
	v_mov_b32_e32 v70, v69
	s_nop 1
	v_permlane32_swap_b32_e32 v70, v69
	s_waitcnt lgkmcnt(0)
	v_add_f32_e32 v69, v69, v70
	v_fmamk_f32 v69, v69, 0x3c800000, v193
	v_rsq_f32_e32 v84, v69
	s_nop 0
	v_pk_mul_f32 v[64:65], v[64:65], v[84:85] op_sel_hi:[1,0]
	v_pk_mul_f32 v[60:61], v[60:61], v[84:85] op_sel_hi:[1,0]
	v_pk_mul_f32 v[56:57], v[56:57], v[84:85] op_sel_hi:[1,0]
	v_pk_mul_f32 v[52:53], v[52:53], v[84:85] op_sel_hi:[1,0]
	v_pk_mul_f32 v[70:71], v[36:37], v[64:65]
	v_pk_mul_f32 v[64:65], v[66:67], v[84:85] op_sel_hi:[1,0]
	v_pk_mul_f32 v[74:75], v[24:25], v[60:61]
	v_pk_mul_f32 v[60:61], v[62:63], v[84:85] op_sel_hi:[1,0]
	v_pk_mul_f32 v[78:79], v[28:29], v[56:57]
	v_pk_mul_f32 v[56:57], v[58:59], v[84:85] op_sel_hi:[1,0]
	v_pk_mul_f32 v[82:83], v[20:21], v[52:53]
	v_pk_mul_f32 v[52:53], v[54:55], v[84:85] op_sel_hi:[1,0]
	v_pk_mul_f32 v[72:73], v[38:39], v[64:65]
	v_pk_mul_f32 v[76:77], v[26:27], v[60:61]
	v_pk_mul_f32 v[80:81], v[30:31], v[56:57]
	v_pk_mul_f32 v[84:85], v[22:23], v[52:53]

.LBB0_320:
	s_waitcnt lgkmcnt(0)
	v_pk_mul_f32 v[48:49], v[48:49], v[54:55] op_sel_hi:[1,0]
	v_pk_mul_f32 v[50:51], v[50:51], v[54:55] op_sel_hi:[1,0]
	v_pk_mul_f32 v[44:45], v[44:45], v[54:55] op_sel_hi:[1,0]
	v_pk_mul_f32 v[46:47], v[46:47], v[54:55] op_sel_hi:[1,0]
	v_pk_mul_f32 v[40:41], v[40:41], v[54:55] op_sel_hi:[1,0]
	v_pk_mul_f32 v[42:43], v[42:43], v[54:55] op_sel_hi:[1,0]
	v_pk_mul_f32 v[32:33], v[32:33], v[54:55] op_sel_hi:[1,0]
	v_pk_mul_f32 v[34:35], v[34:35], v[54:55] op_sel_hi:[1,0]
	s_and_b64 vcc, exec, s[18:19]
	s_mov_b64 s[78:79], -1
	s_cbranch_vccnz .LBB0_327
	s_and_b64 vcc, exec, s[14:15]
	v_mov_b64_e32 v[54:55], v[48:49]
	v_mov_b64_e32 v[56:57], v[50:51]
	v_mov_b64_e32 v[58:59], v[44:45]
	v_mov_b64_e32 v[60:61], v[46:47]
	v_mov_b64_e32 v[62:63], v[40:41]
	v_mov_b64_e32 v[64:65], v[42:43]
	v_mov_b64_e32 v[66:67], v[32:33]
	v_mov_b64_e32 v[68:69], v[34:35]
	s_cbranch_vccnz .LBB0_326
	v_mul_f32_e32 v53, 0x3d922279, v48
	v_fmaak_f32 v53, v48, v53, 0x3fcc422a
	v_mul_f32_e32 v54, 0x3d922279, v49
	v_mul_f32_e32 v53, v48, v53
	v_fmaak_f32 v54, v49, v54, 0x3fcc422a
	v_mul_f32_e32 v53, 0xbfb8aa3b, v53
	v_mul_f32_e32 v54, v49, v54
	v_exp_f32_e32 v53, v53
	v_mul_f32_e32 v54, 0xbfb8aa3b, v54
	v_exp_f32_e32 v55, v54
	v_mul_f32_e32 v56, 0x3d922279, v51
	v_add_f32_e32 v53, 1.0, v53
	v_rcp_f32_e32 v54, v53
	v_add_f32_e32 v53, 1.0, v55
	v_rcp_f32_e32 v55, v53
	v_mul_f32_e32 v53, 0x3d922279, v50
	v_fmaak_f32 v53, v50, v53, 0x3fcc422a
	v_mul_f32_e32 v53, v50, v53
	v_fmaak_f32 v56, v51, v56, 0x3fcc422a
	v_mul_f32_e32 v53, 0xbfb8aa3b, v53
	v_mul_f32_e32 v56, v51, v56
	v_exp_f32_e32 v53, v53
	v_mul_f32_e32 v56, 0xbfb8aa3b, v56
	v_exp_f32_e32 v57, v56
	v_mul_f32_e32 v58, 0x3d922279, v45
	v_add_f32_e32 v53, 1.0, v53
	v_rcp_f32_e32 v56, v53
	v_add_f32_e32 v53, 1.0, v57
	v_rcp_f32_e32 v57, v53
	v_mul_f32_e32 v53, 0x3d922279, v44
	v_fmaak_f32 v53, v44, v53, 0x3fcc422a
	v_mul_f32_e32 v53, v44, v53
	v_fmaak_f32 v58, v45, v58, 0x3fcc422a
	v_mul_f32_e32 v53, 0xbfb8aa3b, v53
	v_mul_f32_e32 v58, v45, v58
	v_exp_f32_e32 v53, v53
	v_mul_f32_e32 v58, 0xbfb8aa3b, v58
	v_exp_f32_e32 v59, v58
	v_mul_f32_e32 v60, 0x3d922279, v47
	v_add_f32_e32 v53, 1.0, v53
	v_rcp_f32_e32 v58, v53
	v_add_f32_e32 v53, 1.0, v59
	v_rcp_f32_e32 v59, v53
	v_mul_f32_e32 v53, 0x3d922279, v46
	v_fmaak_f32 v53, v46, v53, 0x3fcc422a
	v_mul_f32_e32 v53, v46, v53
	v_fmaak_f32 v60, v47, v60, 0x3fcc422a
	v_mul_f32_e32 v53, 0xbfb8aa3b, v53
	v_mul_f32_e32 v60, v47, v60
	v_exp_f32_e32 v53, v53
	v_mul_f32_e32 v60, 0xbfb8aa3b, v60
	v_exp_f32_e32 v61, v60
	v_mul_f32_e32 v62, 0x3d922279, v41
	v_add_f32_e32 v53, 1.0, v53
	v_rcp_f32_e32 v60, v53
	v_add_f32_e32 v53, 1.0, v61
	v_rcp_f32_e32 v61, v53
	v_mul_f32_e32 v53, 0x3d922279, v40
	v_fmaak_f32 v53, v40, v53, 0x3fcc422a
	v_mul_f32_e32 v53, v40, v53
	v_fmaak_f32 v62, v41, v62, 0x3fcc422a
	v_mul_f32_e32 v53, 0xbfb8aa3b, v53
	v_mul_f32_e32 v62, v41, v62
	v_exp_f32_e32 v53, v53
	v_mul_f32_e32 v62, 0xbfb8aa3b, v62
	v_exp_f32_e32 v63, v62
	v_mul_f32_e32 v64, 0x3d922279, v43
	v_add_f32_e32 v53, 1.0, v53
	v_rcp_f32_e32 v62, v53
	v_add_f32_e32 v53, 1.0, v63
	v_rcp_f32_e32 v63, v53
	v_mul_f32_e32 v53, 0x3d922279, v42
	v_fmaak_f32 v53, v42, v53, 0x3fcc422a
	v_mul_f32_e32 v53, v42, v53
	v_fmaak_f32 v64, v43, v64, 0x3fcc422a
	v_mul_f32_e32 v53, 0xbfb8aa3b, v53
	v_mul_f32_e32 v64, v43, v64
	v_exp_f32_e32 v53, v53
	v_mul_f32_e32 v64, 0xbfb8aa3b, v64
	v_exp_f32_e32 v65, v64
	v_mul_f32_e32 v66, 0x3d922279, v33
	v_add_f32_e32 v53, 1.0, v53
	v_rcp_f32_e32 v64, v53
	v_add_f32_e32 v53, 1.0, v65
	v_rcp_f32_e32 v65, v53
	v_mul_f32_e32 v53, 0x3d922279, v32
	v_fmaak_f32 v53, v32, v53, 0x3fcc422a
	v_mul_f32_e32 v53, v32, v53
	v_fmaak_f32 v66, v33, v66, 0x3fcc422a
	v_mul_f32_e32 v53, 0xbfb8aa3b, v53
	v_mul_f32_e32 v66, v33, v66
	v_exp_f32_e32 v53, v53
	v_mul_f32_e32 v66, 0xbfb8aa3b, v66
	v_exp_f32_e32 v67, v66
	v_mul_f32_e32 v68, 0x3d922279, v35
	v_add_f32_e32 v53, 1.0, v53
	v_rcp_f32_e32 v66, v53
	v_add_f32_e32 v53, 1.0, v67
	v_rcp_f32_e32 v67, v53
	v_mul_f32_e32 v53, 0x3d922279, v34
	v_fmaak_f32 v53, v34, v53, 0x3fcc422a
	v_mul_f32_e32 v53, v34, v53
	v_fmaak_f32 v68, v35, v68, 0x3fcc422a
	v_mul_f32_e32 v53, 0xbfb8aa3b, v53
	v_mul_f32_e32 v68, v35, v68
	v_exp_f32_e32 v53, v53
	v_mul_f32_e32 v68, 0xbfb8aa3b, v68
	v_exp_f32_e32 v69, v68
	v_pk_mul_f32 v[54:55], v[48:49], v[54:55]
	v_add_f32_e32 v53, 1.0, v53
	v_rcp_f32_e32 v68, v53
	v_add_f32_e32 v53, 1.0, v69
	v_rcp_f32_e32 v69, v53
	v_pk_mul_f32 v[56:57], v[50:51], v[56:57]
	v_pk_mul_f32 v[58:59], v[44:45], v[58:59]
	v_pk_mul_f32 v[60:61], v[46:47], v[60:61]
	v_pk_mul_f32 v[62:63], v[40:41], v[62:63]
	v_pk_mul_f32 v[64:65], v[42:43], v[64:65]
	v_pk_mul_f32 v[66:67], v[32:33], v[66:67]
	s_andn2_b64 vcc, exec, s[76:77]
	v_pk_mul_f32 v[68:69], v[34:35], v[68:69]
	s_cbranch_vccnz .LBB0_326
	v_pk_mul_f32 v[70:71], v[54:55], v[54:55]
	v_pk_mul_f32 v[72:73], v[56:57], v[56:57]
	v_add_f32_e32 v53, v70, v71
	v_add_f32_e32 v53, v72, v53
	v_pk_mul_f32 v[74:75], v[58:59], v[58:59]
	v_add_f32_e32 v53, v73, v53
	v_add_f32_e32 v53, v74, v53
	v_pk_mul_f32 v[76:77], v[60:61], v[60:61]
	v_add_f32_e32 v53, v75, v53
	v_add_f32_e32 v53, v76, v53
	v_pk_mul_f32 v[78:79], v[62:63], v[62:63]
	v_add_f32_e32 v53, v77, v53
	v_add_f32_e32 v53, v78, v53
	v_pk_mul_f32 v[80:81], v[64:65], v[64:65]
	v_add_f32_e32 v53, v79, v53
	v_add_f32_e32 v53, v80, v53
	v_mbcnt_hi_u32_b32 v71, -1, v1
	v_pk_mul_f32 v[82:83], v[66:67], v[66:67]
	v_add_f32_e32 v53, v81, v53
	v_and_b32_e32 v72, 64, v71
	v_add_f32_e32 v53, v82, v53
	v_xor_b32_e32 v70, 16, v71
	v_add_u32_e32 v72, 64, v72
	v_pk_mul_f32 v[84:85], v[68:69], v[68:69]
	v_add_f32_e32 v53, v83, v53
	v_cmp_lt_i32_e32 vcc, v70, v72
	v_add_f32_e32 v53, v84, v53
	v_add_f32_e32 v53, v85, v53
	v_cndmask_b32_e32 v70, v71, v70, vcc
	v_lshlrev_b32_e32 v70, 2, v70
	v_mov_b32_e32 v70, v53
	s_nop 1
	v_permlane16_swap_b32_e32 v70, v53
	s_waitcnt lgkmcnt(0)
	v_add_f32_e32 v70, v53, v70
	v_xor_b32_e32 v53, 32, v71
	v_cmp_lt_i32_e32 vcc, v53, v72
	s_nop 1
	v_cndmask_b32_e32 v53, v71, v53, vcc
	v_lshlrev_b32_e32 v53, 2, v53
	v_mov_b32_e32 v71, v70
	s_nop 1
	v_permlane32_swap_b32_e32 v71, v70
	s_and_saveexec_b64 s[78:79], s[10:11]
	s_cbranch_execz .LBB0_325
	v_ashrrev_i32_e32 v53, 31, v52
	v_lshlrev_b64 v[72:73], 5, v[52:53]
	v_lshl_add_u64 v[72:73], s[64:65], 0, v[72:73]
	s_lshl_b32 s24, s69, 2
	v_lshl_add_u64 v[72:73], v[72:73], 0, s[24:25]
	s_lshl_b32 s24, s21, 2
	v_lshl_add_u64 v[72:73], v[72:73], 0, s[24:25]
	s_waitcnt lgkmcnt(0)
	v_add_f32_e32 v53, v70, v71
	global_store_dword v[72:73], v53, off

.LBB0_327:
	s_andn2_b64 vcc, exec, s[78:79]
	s_cbranch_vccnz .LBB0_329
	v_pk_mul_f32 v[54:55], v[48:49], v[48:49]
	v_pk_mul_f32 v[56:57], v[50:51], v[50:51]
	v_add_f32_e32 v53, v54, v55
	v_add_f32_e32 v53, v56, v53
	v_pk_mul_f32 v[58:59], v[44:45], v[44:45]
	v_add_f32_e32 v53, v57, v53
	v_add_f32_e32 v53, v58, v53
	v_pk_mul_f32 v[60:61], v[46:47], v[46:47]
	v_add_f32_e32 v53, v59, v53
	v_add_f32_e32 v53, v60, v53
	v_pk_mul_f32 v[62:63], v[40:41], v[40:41]
	v_add_f32_e32 v53, v61, v53
	v_add_f32_e32 v53, v62, v53
	v_pk_mul_f32 v[64:65], v[42:43], v[42:43]
	v_add_f32_e32 v53, v63, v53
	v_add_f32_e32 v53, v64, v53
	v_mbcnt_hi_u32_b32 v54, -1, v1
	v_pk_mul_f32 v[66:67], v[32:33], v[32:33]
	v_add_f32_e32 v53, v65, v53
	v_and_b32_e32 v56, 64, v54
	v_add_f32_e32 v53, v66, v53
	v_xor_b32_e32 v55, 16, v54
	v_add_u32_e32 v56, 64, v56
	v_pk_mul_f32 v[68:69], v[34:35], v[34:35]
	v_add_f32_e32 v53, v67, v53
	v_cmp_lt_i32_e32 vcc, v55, v56
	v_add_f32_e32 v53, v68, v53
	v_add_f32_e32 v53, v69, v53
	v_cndmask_b32_e32 v55, v54, v55, vcc
	v_lshlrev_b32_e32 v55, 2, v55
	v_mov_b32_e32 v55, v53
	s_nop 1
	v_permlane16_swap_b32_e32 v55, v53
	s_waitcnt lgkmcnt(0)
	v_add_f32_e32 v53, v53, v55
	v_xor_b32_e32 v55, 32, v54
	v_cmp_lt_i32_e32 vcc, v55, v56
	s_nop 1
	v_cndmask_b32_e32 v54, v54, v55, vcc
	v_lshlrev_b32_e32 v54, 2, v54
	v_mov_b32_e32 v54, v53
	s_nop 1
	v_permlane32_swap_b32_e32 v54, v53
	s_waitcnt lgkmcnt(0)
	v_add_f32_e32 v53, v53, v54
	v_fmamk_f32 v53, v53, 0x3c800000, v193
	v_rsq_f32_e32 v68, v53
	s_nop 0
	v_pk_mul_f32 v[48:49], v[48:49], v[68:69] op_sel_hi:[1,0]
	v_pk_mul_f32 v[44:45], v[44:45], v[68:69] op_sel_hi:[1,0]
	v_pk_mul_f32 v[40:41], v[40:41], v[68:69] op_sel_hi:[1,0]
	v_pk_mul_f32 v[32:33], v[32:33], v[68:69] op_sel_hi:[1,0]
	v_pk_mul_f32 v[54:55], v[36:37], v[48:49]
	v_pk_mul_f32 v[48:49], v[50:51], v[68:69] op_sel_hi:[1,0]
	v_pk_mul_f32 v[58:59], v[24:25], v[44:45]
	v_pk_mul_f32 v[44:45], v[46:47], v[68:69] op_sel_hi:[1,0]
	v_pk_mul_f32 v[62:63], v[28:29], v[40:41]
	v_pk_mul_f32 v[40:41], v[42:43], v[68:69] op_sel_hi:[1,0]
	v_pk_mul_f32 v[66:67], v[20:21], v[32:33]
	v_pk_mul_f32 v[32:33], v[34:35], v[68:69] op_sel_hi:[1,0]
	v_pk_mul_f32 v[56:57], v[38:39], v[48:49]
	v_pk_mul_f32 v[60:61], v[26:27], v[44:45]
	v_pk_mul_f32 v[64:65], v[30:31], v[40:41]
	v_pk_mul_f32 v[68:69], v[22:23], v[32:33]

.LBB0_333:
	s_waitcnt lgkmcnt(0)
	v_pk_mul_f32 v[16:17], v[16:17], v[34:35] op_sel_hi:[1,0]
	v_pk_mul_f32 v[18:19], v[18:19], v[34:35] op_sel_hi:[1,0]
	v_pk_mul_f32 v[12:13], v[12:13], v[34:35] op_sel_hi:[1,0]
	v_pk_mul_f32 v[14:15], v[14:15], v[34:35] op_sel_hi:[1,0]
	v_pk_mul_f32 v[8:9], v[8:9], v[34:35] op_sel_hi:[1,0]
	v_pk_mul_f32 v[10:11], v[10:11], v[34:35] op_sel_hi:[1,0]
	v_pk_mul_f32 v[4:5], v[4:5], v[34:35] op_sel_hi:[1,0]
	v_pk_mul_f32 v[6:7], v[6:7], v[34:35] op_sel_hi:[1,0]
	s_and_b64 vcc, exec, s[18:19]
	s_mov_b64 s[16:17], -1
	s_cbranch_vccnz .LBB0_340
	s_and_b64 vcc, exec, s[14:15]
	v_mov_b64_e32 v[34:35], v[16:17]
	v_mov_b64_e32 v[40:41], v[18:19]
	v_mov_b64_e32 v[42:43], v[12:13]
	v_mov_b64_e32 v[44:45], v[14:15]
	v_mov_b64_e32 v[46:47], v[8:9]
	v_mov_b64_e32 v[48:49], v[10:11]
	v_mov_b64_e32 v[50:51], v[4:5]
	v_mov_b64_e32 v[52:53], v[6:7]
	s_cbranch_vccnz .LBB0_339
	v_mul_f32_e32 v33, 0x3d922279, v16
	v_fmaak_f32 v33, v16, v33, 0x3fcc422a
	v_mul_f32_e32 v34, 0x3d922279, v17
	v_mul_f32_e32 v33, v16, v33
	v_fmaak_f32 v34, v17, v34, 0x3fcc422a
	v_mul_f32_e32 v33, 0xbfb8aa3b, v33
	v_mul_f32_e32 v34, v17, v34
	v_exp_f32_e32 v33, v33
	v_mul_f32_e32 v34, 0xbfb8aa3b, v34
	v_exp_f32_e32 v35, v34
	v_mul_f32_e32 v40, 0x3d922279, v19
	v_add_f32_e32 v33, 1.0, v33
	v_rcp_f32_e32 v34, v33
	v_add_f32_e32 v33, 1.0, v35
	v_rcp_f32_e32 v35, v33
	v_mul_f32_e32 v33, 0x3d922279, v18
	v_fmaak_f32 v33, v18, v33, 0x3fcc422a
	v_mul_f32_e32 v33, v18, v33
	v_fmaak_f32 v40, v19, v40, 0x3fcc422a
	v_mul_f32_e32 v33, 0xbfb8aa3b, v33
	v_mul_f32_e32 v40, v19, v40
	v_exp_f32_e32 v33, v33
	v_mul_f32_e32 v40, 0xbfb8aa3b, v40
	v_exp_f32_e32 v41, v40
	v_mul_f32_e32 v42, 0x3d922279, v13
	v_add_f32_e32 v33, 1.0, v33
	v_rcp_f32_e32 v40, v33
	v_add_f32_e32 v33, 1.0, v41
	v_rcp_f32_e32 v41, v33
	v_mul_f32_e32 v33, 0x3d922279, v12
	v_fmaak_f32 v33, v12, v33, 0x3fcc422a
	v_mul_f32_e32 v33, v12, v33
	v_fmaak_f32 v42, v13, v42, 0x3fcc422a
	v_mul_f32_e32 v33, 0xbfb8aa3b, v33
	v_mul_f32_e32 v42, v13, v42
	v_exp_f32_e32 v33, v33
	v_mul_f32_e32 v42, 0xbfb8aa3b, v42
	v_exp_f32_e32 v43, v42
	v_mul_f32_e32 v44, 0x3d922279, v15
	v_add_f32_e32 v33, 1.0, v33
	v_rcp_f32_e32 v42, v33
	v_add_f32_e32 v33, 1.0, v43
	v_rcp_f32_e32 v43, v33
	v_mul_f32_e32 v33, 0x3d922279, v14
	v_fmaak_f32 v33, v14, v33, 0x3fcc422a
	v_mul_f32_e32 v33, v14, v33
	v_fmaak_f32 v44, v15, v44, 0x3fcc422a
	v_mul_f32_e32 v33, 0xbfb8aa3b, v33
	v_mul_f32_e32 v44, v15, v44
	v_exp_f32_e32 v33, v33
	v_mul_f32_e32 v44, 0xbfb8aa3b, v44
	v_exp_f32_e32 v45, v44
	v_mul_f32_e32 v46, 0x3d922279, v9
	v_add_f32_e32 v33, 1.0, v33
	v_rcp_f32_e32 v44, v33
	v_add_f32_e32 v33, 1.0, v45
	v_rcp_f32_e32 v45, v33
	v_mul_f32_e32 v33, 0x3d922279, v8
	v_fmaak_f32 v33, v8, v33, 0x3fcc422a
	v_mul_f32_e32 v33, v8, v33
	v_fmaak_f32 v46, v9, v46, 0x3fcc422a
	v_mul_f32_e32 v33, 0xbfb8aa3b, v33
	v_mul_f32_e32 v46, v9, v46
	v_exp_f32_e32 v33, v33
	v_mul_f32_e32 v46, 0xbfb8aa3b, v46
	v_exp_f32_e32 v47, v46
	v_mul_f32_e32 v48, 0x3d922279, v11
	v_add_f32_e32 v33, 1.0, v33
	v_rcp_f32_e32 v46, v33
	v_add_f32_e32 v33, 1.0, v47
	v_rcp_f32_e32 v47, v33
	v_mul_f32_e32 v33, 0x3d922279, v10
	v_fmaak_f32 v33, v10, v33, 0x3fcc422a
	v_mul_f32_e32 v33, v10, v33
	v_fmaak_f32 v48, v11, v48, 0x3fcc422a
	v_mul_f32_e32 v33, 0xbfb8aa3b, v33
	v_mul_f32_e32 v48, v11, v48
	v_exp_f32_e32 v33, v33
	v_mul_f32_e32 v48, 0xbfb8aa3b, v48
	v_exp_f32_e32 v49, v48
	v_mul_f32_e32 v50, 0x3d922279, v5
	v_add_f32_e32 v33, 1.0, v33
	v_rcp_f32_e32 v48, v33
	v_add_f32_e32 v33, 1.0, v49
	v_rcp_f32_e32 v49, v33
	v_mul_f32_e32 v33, 0x3d922279, v4
	v_fmaak_f32 v33, v4, v33, 0x3fcc422a
	v_mul_f32_e32 v33, v4, v33
	v_fmaak_f32 v50, v5, v50, 0x3fcc422a
	v_mul_f32_e32 v33, 0xbfb8aa3b, v33
	v_mul_f32_e32 v50, v5, v50
	v_exp_f32_e32 v33, v33
	v_mul_f32_e32 v50, 0xbfb8aa3b, v50
	v_exp_f32_e32 v51, v50
	v_mul_f32_e32 v52, 0x3d922279, v7
	v_add_f32_e32 v33, 1.0, v33
	v_rcp_f32_e32 v50, v33
	v_add_f32_e32 v33, 1.0, v51
	v_rcp_f32_e32 v51, v33
	v_mul_f32_e32 v33, 0x3d922279, v6
	v_fmaak_f32 v33, v6, v33, 0x3fcc422a
	v_mul_f32_e32 v33, v6, v33
	v_fmaak_f32 v52, v7, v52, 0x3fcc422a
	v_mul_f32_e32 v33, 0xbfb8aa3b, v33
	v_mul_f32_e32 v52, v7, v52
	v_exp_f32_e32 v33, v33
	v_mul_f32_e32 v52, 0xbfb8aa3b, v52
	v_exp_f32_e32 v53, v52
	v_pk_mul_f32 v[34:35], v[16:17], v[34:35]
	v_add_f32_e32 v33, 1.0, v33
	v_rcp_f32_e32 v52, v33
	v_add_f32_e32 v33, 1.0, v53
	v_rcp_f32_e32 v53, v33
	v_pk_mul_f32 v[40:41], v[18:19], v[40:41]
	v_pk_mul_f32 v[42:43], v[12:13], v[42:43]
	v_pk_mul_f32 v[44:45], v[14:15], v[44:45]
	v_pk_mul_f32 v[46:47], v[8:9], v[46:47]
	v_pk_mul_f32 v[48:49], v[10:11], v[48:49]
	v_pk_mul_f32 v[50:51], v[4:5], v[50:51]
	s_andn2_b64 vcc, exec, s[76:77]
	v_pk_mul_f32 v[52:53], v[6:7], v[52:53]
	s_cbranch_vccnz .LBB0_339
	v_pk_mul_f32 v[54:55], v[34:35], v[34:35]
	v_pk_mul_f32 v[56:57], v[40:41], v[40:41]
	v_add_f32_e32 v33, v54, v55
	v_add_f32_e32 v33, v56, v33
	v_pk_mul_f32 v[58:59], v[42:43], v[42:43]
	v_add_f32_e32 v33, v57, v33
	v_add_f32_e32 v33, v58, v33
	v_pk_mul_f32 v[60:61], v[44:45], v[44:45]
	v_add_f32_e32 v33, v59, v33
	v_add_f32_e32 v33, v60, v33
	v_pk_mul_f32 v[62:63], v[46:47], v[46:47]
	v_add_f32_e32 v33, v61, v33
	v_add_f32_e32 v33, v62, v33
	v_pk_mul_f32 v[64:65], v[48:49], v[48:49]
	v_add_f32_e32 v33, v63, v33
	v_add_f32_e32 v33, v64, v33
	v_mbcnt_hi_u32_b32 v55, -1, v1
	v_pk_mul_f32 v[66:67], v[50:51], v[50:51]
	v_add_f32_e32 v33, v65, v33
	v_and_b32_e32 v56, 64, v55
	v_add_f32_e32 v33, v66, v33
	v_xor_b32_e32 v54, 16, v55
	v_add_u32_e32 v56, 64, v56
	v_pk_mul_f32 v[68:69], v[52:53], v[52:53]
	v_add_f32_e32 v33, v67, v33
	v_cmp_lt_i32_e32 vcc, v54, v56
	v_add_f32_e32 v33, v68, v33
	v_add_f32_e32 v33, v69, v33
	v_cndmask_b32_e32 v54, v55, v54, vcc
	v_lshlrev_b32_e32 v54, 2, v54
	v_mov_b32_e32 v54, v33
	s_nop 1
	v_permlane16_swap_b32_e32 v54, v33
	s_waitcnt lgkmcnt(0)
	v_add_f32_e32 v54, v33, v54
	v_xor_b32_e32 v33, 32, v55
	v_cmp_lt_i32_e32 vcc, v33, v56
	s_nop 1
	v_cndmask_b32_e32 v33, v55, v33, vcc
	v_lshlrev_b32_e32 v33, 2, v33
	v_mov_b32_e32 v55, v54
	s_nop 1
	v_permlane32_swap_b32_e32 v55, v54
	s_and_saveexec_b64 s[14:15], s[10:11]
	s_cbranch_execz .LBB0_338
	v_ashrrev_i32_e32 v33, 31, v32
	v_lshlrev_b64 v[56:57], 5, v[32:33]
	v_lshl_add_u64 v[56:57], s[64:65], 0, v[56:57]
	s_lshl_b32 s24, s69, 2
	v_lshl_add_u64 v[56:57], v[56:57], 0, s[24:25]
	s_lshl_b32 s24, s21, 2
	v_lshl_add_u64 v[56:57], v[56:57], 0, s[24:25]
	s_waitcnt lgkmcnt(0)
	v_add_f32_e32 v33, v54, v55
	global_store_dword v[56:57], v33, off

.LBB0_340:
	s_andn2_b64 vcc, exec, s[16:17]
	s_cbranch_vccnz .LBB0_342
	v_pk_mul_f32 v[34:35], v[16:17], v[16:17]
	v_pk_mul_f32 v[40:41], v[18:19], v[18:19]
	v_add_f32_e32 v33, v34, v35
	v_add_f32_e32 v33, v40, v33
	v_pk_mul_f32 v[42:43], v[12:13], v[12:13]
	v_add_f32_e32 v33, v41, v33
	v_add_f32_e32 v33, v42, v33
	v_pk_mul_f32 v[44:45], v[14:15], v[14:15]
	v_add_f32_e32 v33, v43, v33
	v_add_f32_e32 v33, v44, v33
	v_pk_mul_f32 v[46:47], v[8:9], v[8:9]
	v_add_f32_e32 v33, v45, v33
	v_add_f32_e32 v33, v46, v33
	v_pk_mul_f32 v[48:49], v[10:11], v[10:11]
	v_add_f32_e32 v33, v47, v33
	v_add_f32_e32 v33, v48, v33
	v_mbcnt_hi_u32_b32 v34, -1, v1
	v_pk_mul_f32 v[50:51], v[4:5], v[4:5]
	v_add_f32_e32 v33, v49, v33
	v_and_b32_e32 v40, 64, v34
	v_add_f32_e32 v33, v50, v33
	v_xor_b32_e32 v35, 16, v34
	v_add_u32_e32 v40, 64, v40
	v_pk_mul_f32 v[52:53], v[6:7], v[6:7]
	v_add_f32_e32 v33, v51, v33
	v_cmp_lt_i32_e32 vcc, v35, v40
	v_add_f32_e32 v33, v52, v33
	v_add_f32_e32 v33, v53, v33
	v_cndmask_b32_e32 v35, v34, v35, vcc
	v_lshlrev_b32_e32 v35, 2, v35
	v_mov_b32_e32 v35, v33
	s_nop 1
	v_permlane16_swap_b32_e32 v35, v33
	s_waitcnt lgkmcnt(0)
	v_add_f32_e32 v33, v33, v35
	v_xor_b32_e32 v35, 32, v34
	v_cmp_lt_i32_e32 vcc, v35, v40
	s_nop 1
	v_cndmask_b32_e32 v34, v34, v35, vcc
	v_lshlrev_b32_e32 v34, 2, v34
	v_mov_b32_e32 v34, v33
	s_nop 1
	v_permlane32_swap_b32_e32 v34, v33
	s_waitcnt lgkmcnt(0)
	v_add_f32_e32 v33, v33, v34
	v_fmamk_f32 v33, v33, 0x3c800000, v193
	v_rsq_f32_e32 v52, v33
	s_nop 0
	v_pk_mul_f32 v[16:17], v[16:17], v[52:53] op_sel_hi:[1,0]
	v_pk_mul_f32 v[12:13], v[12:13], v[52:53] op_sel_hi:[1,0]
	v_pk_mul_f32 v[8:9], v[8:9], v[52:53] op_sel_hi:[1,0]
	v_pk_mul_f32 v[4:5], v[4:5], v[52:53] op_sel_hi:[1,0]
	v_pk_mul_f32 v[34:35], v[36:37], v[16:17]
	v_pk_mul_f32 v[16:17], v[18:19], v[52:53] op_sel_hi:[1,0]
	v_pk_mul_f32 v[42:43], v[24:25], v[12:13]
	v_pk_mul_f32 v[12:13], v[14:15], v[52:53] op_sel_hi:[1,0]
	v_pk_mul_f32 v[46:47], v[28:29], v[8:9]
	v_pk_mul_f32 v[8:9], v[10:11], v[52:53] op_sel_hi:[1,0]
	v_pk_mul_f32 v[50:51], v[20:21], v[4:5]
	v_pk_mul_f32 v[4:5], v[6:7], v[52:53] op_sel_hi:[1,0]
	v_pk_mul_f32 v[40:41], v[38:39], v[16:17]
	v_pk_mul_f32 v[44:45], v[26:27], v[12:13]
	v_pk_mul_f32 v[48:49], v[30:31], v[8:9]
	v_pk_mul_f32 v[52:53], v[22:23], v[4:5]
